# barrier trims + every K-loop MFMA group 8-byte aligned (pad before the pre-MMA barrier)
# speedup vs baseline: 1.0042x; 1.0042x over previous
.LBB0_262:
	s_add_i32 vcc_lo, s38, 2
	s_add_u32 s39, s10, 0xfff00080
	s_addc_u32 s66, s11, -1
	s_add_i32 s67, 0, 0x10000
	s_cmp_eq_u32 s35, s38
	s_cselect_b32 s87, s53, s66
	s_cselect_b32 s86, s52, s39
	s_cselect_b32 s39, s13, s49
	s_cselect_b32 s38, s15, s40
	s_add_i32 vcc_hi, 0, 0x14000
	v_add_u32_e32 v142, s67, v1
	v_add_u32_e32 v180, vcc_hi, v1
	ds_read_b128 v[130:133], v142
	ds_read_b128 v[134:137], v142 offset:1024
	ds_read_b128 v[138:141], v142 offset:2048
	ds_read_b128 v[142:145], v142 offset:3072
	ds_read_b128 v[168:171], v180
	ds_read_b128 v[172:175], v180 offset:1024
	ds_read_b128 v[176:179], v180 offset:2048
	ds_read_b128 v[180:183], v180 offset:3072
	v_lshl_add_u64 v[184:185], s[10:11], 0, v[164:165]
	s_add_i32 m0, s85, 0xc000
	ds_read_b128 v[198:201], v197
	ds_read_b128 v[202:205], v197 offset:1024
	ds_read_b128 v[206:209], v197 offset:2048
	ds_read_b128 v[210:213], v197 offset:3072
	ds_read_b128 v[214:217], v197 offset:4096
	ds_read_b128 v[218:221], v197 offset:5120
	ds_read_b128 v[222:225], v197 offset:6144
	ds_read_b128 v[226:229], v197 offset:7168
	global_load_lds_dwordx4 v[184:185], off
	v_lshl_add_u64 v[184:185], s[10:11], 0, v[166:167]
	s_add_i32 m0, s85, 0xe000
	s_nop 0
	global_load_lds_dwordx4 v[184:185], off
	s_waitcnt vmcnt(8)
	s_waitcnt lgkmcnt(0)
	.p2alignl 3, 3212836864
	s_setprio 1
	s_barrier
	v_mfma_f32_16x16x32_bf16 v[114:117], v[130:133], v[198:201], v[114:117]
	v_mfma_f32_16x16x32_bf16 v[118:121], v[138:141], v[198:201], v[118:121]
	v_mfma_f32_16x16x32_bf16 v[102:105], v[130:133], v[206:209], v[102:105]
	v_mfma_f32_16x16x32_bf16 v[98:101], v[138:141], v[206:209], v[98:101]
	v_mfma_f32_16x16x32_bf16 v[86:89], v[130:133], v[214:217], v[86:89]
	v_mfma_f32_16x16x32_bf16 v[82:85], v[138:141], v[214:217], v[82:85]
	v_mfma_f32_16x16x32_bf16 v[54:57], v[130:133], v[222:225], v[54:57]
	v_mfma_f32_16x16x32_bf16 v[50:53], v[138:141], v[222:225], v[50:53]
	v_mfma_f32_16x16x32_bf16 v[114:117], v[134:137], v[202:205], v[114:117]
	v_mfma_f32_16x16x32_bf16 v[118:121], v[142:145], v[202:205], v[118:121]
	v_mfma_f32_16x16x32_bf16 v[102:105], v[134:137], v[210:213], v[102:105]
	v_mfma_f32_16x16x32_bf16 v[98:101], v[142:145], v[210:213], v[98:101]
	v_mfma_f32_16x16x32_bf16 v[86:89], v[134:137], v[218:221], v[86:89]
	v_mfma_f32_16x16x32_bf16 v[82:85], v[142:145], v[218:221], v[82:85]
	v_mfma_f32_16x16x32_bf16 v[54:57], v[134:137], v[226:229], v[54:57]
	v_mfma_f32_16x16x32_bf16 v[50:53], v[142:145], v[226:229], v[50:53]
	s_setprio 0
	s_setprio 1
	v_mfma_f32_16x16x32_bf16 v[126:129], v[168:171], v[198:201], v[126:129]
	v_mfma_f32_16x16x32_bf16 v[122:125], v[176:179], v[198:201], v[122:125]
	v_mfma_f32_16x16x32_bf16 v[110:113], v[168:171], v[206:209], v[110:113]
	v_mfma_f32_16x16x32_bf16 v[106:109], v[176:179], v[206:209], v[106:109]
	v_mfma_f32_16x16x32_bf16 v[94:97], v[168:171], v[214:217], v[94:97]
	v_mfma_f32_16x16x32_bf16 v[90:93], v[176:179], v[214:217], v[90:93]
	v_mfma_f32_16x16x32_bf16 v[70:73], v[168:171], v[222:225], v[70:73]
	v_mfma_f32_16x16x32_bf16 v[66:69], v[176:179], v[222:225], v[66:69]
	v_mfma_f32_16x16x32_bf16 v[126:129], v[172:175], v[202:205], v[126:129]
	v_mfma_f32_16x16x32_bf16 v[122:125], v[180:183], v[202:205], v[122:125]
	v_mfma_f32_16x16x32_bf16 v[110:113], v[172:175], v[210:213], v[110:113]
	v_mfma_f32_16x16x32_bf16 v[106:109], v[180:183], v[210:213], v[106:109]
	v_mfma_f32_16x16x32_bf16 v[94:97], v[172:175], v[218:221], v[94:97]
	v_mfma_f32_16x16x32_bf16 v[90:93], v[180:183], v[218:221], v[90:93]
	v_mfma_f32_16x16x32_bf16 v[70:73], v[172:175], v[226:229], v[70:73]
	v_mfma_f32_16x16x32_bf16 v[66:69], v[180:183], v[226:229], v[66:69]
	s_barrier
	s_setprio 0
	s_add_i32 s66, s67, s97
	v_lshl_add_u64 v[184:185], s[38:39], 0, v[156:157]
	s_mov_b32 m0, s66
	ds_read_b128 v[198:201], v197 offset:16384
	ds_read_b128 v[202:205], v197 offset:17408
	ds_read_b128 v[206:209], v197 offset:18432
	ds_read_b128 v[210:213], v197 offset:19456
	ds_read_b128 v[214:217], v197 offset:20480
	ds_read_b128 v[218:221], v197 offset:21504
	ds_read_b128 v[222:225], v197 offset:22528
	ds_read_b128 v[226:229], v197 offset:23552
	global_load_lds_dwordx4 v[184:185], off
	s_add_i32 m0, s66, 0x2000
	s_add_u32 s66, s38, 0x100000
	v_lshl_add_u64 v[230:231], s[38:39], 0, v[160:161]
	s_addc_u32 s67, s39, 0
	s_add_i32 vcc_hi, vcc_hi, s97
	global_load_lds_dwordx4 v[230:231], off
	v_lshl_add_u64 v[232:233], s[66:67], 0, v[156:157]
	s_mov_b32 m0, vcc_hi
	v_lshl_add_u64 v[234:235], s[86:87], 0, v[158:159]
	global_load_lds_dwordx4 v[232:233], off
	v_lshl_add_u64 v[232:233], s[66:67], 0, v[160:161]
	s_add_i32 m0, vcc_hi, 0x2000
	s_nop 0
	global_load_lds_dwordx4 v[232:233], off
	v_lshl_add_u64 v[232:233], s[86:87], 0, v[154:155]
	s_mov_b32 m0, s85
	s_nop 0
	global_load_lds_dwordx4 v[232:233], off
	s_mov_b32 m0, s92
	s_nop 0
	global_load_lds_dwordx4 v[234:235], off
	s_waitcnt vmcnt(8)
	s_waitcnt lgkmcnt(0)
	.p2alignl 3, 3212836864
	s_setprio 1
	s_barrier
	v_mfma_f32_16x16x32_bf16 v[62:65], v[130:133], v[198:201], v[62:65]
	v_mfma_f32_16x16x32_bf16 v[58:61], v[138:141], v[198:201], v[58:61]
	v_mfma_f32_16x16x32_bf16 v[38:41], v[130:133], v[206:209], v[38:41]
	v_mfma_f32_16x16x32_bf16 v[34:37], v[138:141], v[206:209], v[34:37]
	v_mfma_f32_16x16x32_bf16 v[22:25], v[130:133], v[214:217], v[22:25]
	v_mfma_f32_16x16x32_bf16 v[18:21], v[138:141], v[214:217], v[18:21]
	v_mfma_f32_16x16x32_bf16 v[6:9], v[130:133], v[222:225], v[6:9]
	v_mfma_f32_16x16x32_bf16 v[2:5], v[138:141], v[222:225], v[2:5]
	v_mfma_f32_16x16x32_bf16 v[62:65], v[134:137], v[202:205], v[62:65]
	v_mfma_f32_16x16x32_bf16 v[58:61], v[142:145], v[202:205], v[58:61]
	v_mfma_f32_16x16x32_bf16 v[38:41], v[134:137], v[210:213], v[38:41]
	v_mfma_f32_16x16x32_bf16 v[34:37], v[142:145], v[210:213], v[34:37]
	v_mfma_f32_16x16x32_bf16 v[22:25], v[134:137], v[218:221], v[22:25]
	v_mfma_f32_16x16x32_bf16 v[18:21], v[142:145], v[218:221], v[18:21]
	v_mfma_f32_16x16x32_bf16 v[6:9], v[134:137], v[226:229], v[6:9]
	v_mfma_f32_16x16x32_bf16 v[2:5], v[142:145], v[226:229], v[2:5]
	s_setprio 0
	s_setprio 1
	v_mfma_f32_16x16x32_bf16 v[78:81], v[168:171], v[198:201], v[78:81]
	v_mfma_f32_16x16x32_bf16 v[74:77], v[176:179], v[198:201], v[74:77]
	v_mfma_f32_16x16x32_bf16 v[46:49], v[168:171], v[206:209], v[46:49]
	v_mfma_f32_16x16x32_bf16 v[42:45], v[176:179], v[206:209], v[42:45]
	v_mfma_f32_16x16x32_bf16 v[30:33], v[168:171], v[214:217], v[30:33]
	v_mfma_f32_16x16x32_bf16 v[26:29], v[176:179], v[214:217], v[26:29]
	v_mfma_f32_16x16x32_bf16 v[14:17], v[168:171], v[222:225], v[14:17]
	v_mfma_f32_16x16x32_bf16 v[10:13], v[176:179], v[222:225], v[10:13]
	v_mfma_f32_16x16x32_bf16 v[78:81], v[172:175], v[202:205], v[78:81]
	v_mfma_f32_16x16x32_bf16 v[74:77], v[180:183], v[202:205], v[74:77]
	v_mfma_f32_16x16x32_bf16 v[46:49], v[172:175], v[210:213], v[46:49]
	v_mfma_f32_16x16x32_bf16 v[42:45], v[180:183], v[210:213], v[42:45]
	v_mfma_f32_16x16x32_bf16 v[30:33], v[172:175], v[218:221], v[30:33]
	v_mfma_f32_16x16x32_bf16 v[26:29], v[180:183], v[218:221], v[26:29]
	v_mfma_f32_16x16x32_bf16 v[14:17], v[172:175], v[226:229], v[14:17]
	v_mfma_f32_16x16x32_bf16 v[10:13], v[180:183], v[226:229], v[10:13]
	s_barrier
	s_setprio 0
	s_add_i32 vcc_hi, 0, 0x18000
	s_add_i32 s56, 0, 0x1c000
	v_add_u32_e32 v142, vcc_hi, v1
	v_add_u32_e32 v180, s56, v1
	ds_read_b128 v[130:133], v142
	ds_read_b128 v[134:137], v142 offset:1024
	ds_read_b128 v[138:141], v142 offset:2048
	ds_read_b128 v[142:145], v142 offset:3072
	ds_read_b128 v[168:171], v180
	ds_read_b128 v[172:175], v180 offset:1024
	ds_read_b128 v[176:179], v180 offset:2048
	ds_read_b128 v[180:183], v180 offset:3072
	s_add_u32 s66, s86, 0x100000
	s_addc_u32 s67, s87, 0
	s_mov_b32 m0, s93
	v_lshl_add_u64 v[236:237], s[66:67], 0, v[154:155]
	ds_read_b128 v[198:201], v197 offset:32768
	ds_read_b128 v[202:205], v197 offset:33792
	ds_read_b128 v[206:209], v197 offset:34816
	ds_read_b128 v[210:213], v197 offset:35840
	ds_read_b128 v[214:217], v197 offset:36864
	ds_read_b128 v[218:221], v197 offset:37888
	ds_read_b128 v[222:225], v197 offset:38912
	ds_read_b128 v[226:229], v197 offset:39936
	global_load_lds_dwordx4 v[236:237], off
	v_lshl_add_u64 v[236:237], s[66:67], 0, v[158:159]
	s_mov_b32 m0, s42
	s_nop 0
	global_load_lds_dwordx4 v[236:237], off
	s_waitcnt vmcnt(8)
	s_waitcnt lgkmcnt(0)
	.p2alignl 3, 3212836864
	s_setprio 1
	s_barrier
	v_mfma_f32_16x16x32_bf16 v[114:117], v[130:133], v[198:201], v[114:117]
	v_mfma_f32_16x16x32_bf16 v[118:121], v[138:141], v[198:201], v[118:121]
	v_mfma_f32_16x16x32_bf16 v[102:105], v[130:133], v[206:209], v[102:105]
	v_mfma_f32_16x16x32_bf16 v[98:101], v[138:141], v[206:209], v[98:101]
	v_mfma_f32_16x16x32_bf16 v[86:89], v[130:133], v[214:217], v[86:89]
	v_mfma_f32_16x16x32_bf16 v[82:85], v[138:141], v[214:217], v[82:85]
	v_mfma_f32_16x16x32_bf16 v[54:57], v[130:133], v[222:225], v[54:57]
	v_mfma_f32_16x16x32_bf16 v[50:53], v[138:141], v[222:225], v[50:53]
	v_mfma_f32_16x16x32_bf16 v[114:117], v[134:137], v[202:205], v[114:117]
	v_mfma_f32_16x16x32_bf16 v[118:121], v[142:145], v[202:205], v[118:121]
	v_mfma_f32_16x16x32_bf16 v[102:105], v[134:137], v[210:213], v[102:105]
	v_mfma_f32_16x16x32_bf16 v[98:101], v[142:145], v[210:213], v[98:101]
	v_mfma_f32_16x16x32_bf16 v[86:89], v[134:137], v[218:221], v[86:89]
	v_mfma_f32_16x16x32_bf16 v[82:85], v[142:145], v[218:221], v[82:85]
	v_mfma_f32_16x16x32_bf16 v[54:57], v[134:137], v[226:229], v[54:57]
	v_mfma_f32_16x16x32_bf16 v[50:53], v[142:145], v[226:229], v[50:53]
	s_setprio 0
	s_setprio 1
	v_mfma_f32_16x16x32_bf16 v[126:129], v[168:171], v[198:201], v[126:129]
	v_mfma_f32_16x16x32_bf16 v[122:125], v[176:179], v[198:201], v[122:125]
	v_mfma_f32_16x16x32_bf16 v[110:113], v[168:171], v[206:209], v[110:113]
	v_mfma_f32_16x16x32_bf16 v[106:109], v[176:179], v[206:209], v[106:109]
	v_mfma_f32_16x16x32_bf16 v[94:97], v[168:171], v[214:217], v[94:97]
	v_mfma_f32_16x16x32_bf16 v[90:93], v[176:179], v[214:217], v[90:93]
	v_mfma_f32_16x16x32_bf16 v[70:73], v[168:171], v[222:225], v[70:73]
	v_mfma_f32_16x16x32_bf16 v[66:69], v[176:179], v[222:225], v[66:69]
	v_mfma_f32_16x16x32_bf16 v[126:129], v[172:175], v[202:205], v[126:129]
	v_mfma_f32_16x16x32_bf16 v[122:125], v[180:183], v[202:205], v[122:125]
	v_mfma_f32_16x16x32_bf16 v[110:113], v[172:175], v[210:213], v[110:113]
	v_mfma_f32_16x16x32_bf16 v[106:109], v[180:183], v[210:213], v[106:109]
	v_mfma_f32_16x16x32_bf16 v[94:97], v[172:175], v[218:221], v[94:97]
	v_mfma_f32_16x16x32_bf16 v[90:93], v[180:183], v[218:221], v[90:93]
	v_mfma_f32_16x16x32_bf16 v[70:73], v[172:175], v[226:229], v[70:73]
	v_mfma_f32_16x16x32_bf16 v[66:69], v[180:183], v[226:229], v[66:69]
	s_barrier
	s_setprio 0
	s_add_i32 s57, vcc_hi, s97
	v_lshl_add_u64 v[184:185], v[184:185], 0, s[94:95]
	s_mov_b32 m0, s57
	ds_read_b128 v[198:201], v197 offset:49152
	ds_read_b128 v[202:205], v197 offset:50176
	ds_read_b128 v[206:209], v197 offset:51200
	ds_read_b128 v[210:213], v197 offset:52224
	ds_read_b128 v[214:217], v197 offset:53248
	ds_read_b128 v[218:221], v197 offset:54272
	ds_read_b128 v[222:225], v197 offset:55296
	ds_read_b128 v[226:229], v197 offset:56320
	global_load_lds_dwordx4 v[184:185], off
	s_add_i32 m0, s57, 0x2000
	s_add_u32 s38, s38, 0x100080
	v_lshl_add_u64 v[184:185], v[230:231], 0, s[94:95]
	s_addc_u32 s39, s39, 0
	s_add_i32 s56, s56, s97
	global_load_lds_dwordx4 v[184:185], off
	v_lshl_add_u64 v[184:185], s[38:39], 0, v[156:157]
	s_mov_b32 m0, s56
	s_nop 0
	global_load_lds_dwordx4 v[184:185], off
	v_lshl_add_u64 v[184:185], s[38:39], 0, v[160:161]
	s_add_i32 m0, s56, 0x2000
	s_nop 0
	global_load_lds_dwordx4 v[184:185], off
	v_lshl_add_u64 v[184:185], v[232:233], 0, s[94:95]
	s_mov_b32 m0, s43
	s_nop 0
	global_load_lds_dwordx4 v[184:185], off
	v_lshl_add_u64 v[184:185], v[234:235], 0, s[94:95]
	s_mov_b32 m0, s90
	s_nop 0
	global_load_lds_dwordx4 v[184:185], off
	s_waitcnt vmcnt(8)
	s_waitcnt lgkmcnt(0)
	.p2alignl 3, 3212836864
	s_setprio 1
	s_barrier
	v_mfma_f32_16x16x32_bf16 v[62:65], v[130:133], v[198:201], v[62:65]
	v_mfma_f32_16x16x32_bf16 v[58:61], v[138:141], v[198:201], v[58:61]
	v_mfma_f32_16x16x32_bf16 v[38:41], v[130:133], v[206:209], v[38:41]
	v_mfma_f32_16x16x32_bf16 v[34:37], v[138:141], v[206:209], v[34:37]
	v_mfma_f32_16x16x32_bf16 v[22:25], v[130:133], v[214:217], v[22:25]
	v_mfma_f32_16x16x32_bf16 v[18:21], v[138:141], v[214:217], v[18:21]
	v_mfma_f32_16x16x32_bf16 v[6:9], v[130:133], v[222:225], v[6:9]
	v_mfma_f32_16x16x32_bf16 v[2:5], v[138:141], v[222:225], v[2:5]
	v_mfma_f32_16x16x32_bf16 v[62:65], v[134:137], v[202:205], v[62:65]
	v_mfma_f32_16x16x32_bf16 v[58:61], v[142:145], v[202:205], v[58:61]
	v_mfma_f32_16x16x32_bf16 v[38:41], v[134:137], v[210:213], v[38:41]
	v_mfma_f32_16x16x32_bf16 v[34:37], v[142:145], v[210:213], v[34:37]
	v_mfma_f32_16x16x32_bf16 v[22:25], v[134:137], v[218:221], v[22:25]
	v_mfma_f32_16x16x32_bf16 v[18:21], v[142:145], v[218:221], v[18:21]
	v_mfma_f32_16x16x32_bf16 v[6:9], v[134:137], v[226:229], v[6:9]
	v_mfma_f32_16x16x32_bf16 v[2:5], v[142:145], v[226:229], v[2:5]
	s_setprio 0
	s_setprio 1
	v_mfma_f32_16x16x32_bf16 v[78:81], v[168:171], v[198:201], v[78:81]
	v_mfma_f32_16x16x32_bf16 v[74:77], v[176:179], v[198:201], v[74:77]
	v_mfma_f32_16x16x32_bf16 v[46:49], v[168:171], v[206:209], v[46:49]
	v_mfma_f32_16x16x32_bf16 v[42:45], v[176:179], v[206:209], v[42:45]
	v_mfma_f32_16x16x32_bf16 v[30:33], v[168:171], v[214:217], v[30:33]
	v_mfma_f32_16x16x32_bf16 v[26:29], v[176:179], v[214:217], v[26:29]
	v_mfma_f32_16x16x32_bf16 v[14:17], v[168:171], v[222:225], v[14:17]
	v_mfma_f32_16x16x32_bf16 v[10:13], v[176:179], v[222:225], v[10:13]
	v_mfma_f32_16x16x32_bf16 v[78:81], v[172:175], v[202:205], v[78:81]
	v_mfma_f32_16x16x32_bf16 v[74:77], v[180:183], v[202:205], v[74:77]
	v_mfma_f32_16x16x32_bf16 v[46:49], v[172:175], v[210:213], v[46:49]
	v_mfma_f32_16x16x32_bf16 v[42:45], v[180:183], v[210:213], v[42:45]
	v_mfma_f32_16x16x32_bf16 v[30:33], v[172:175], v[218:221], v[30:33]
	v_mfma_f32_16x16x32_bf16 v[26:29], v[180:183], v[218:221], v[26:29]
	v_mfma_f32_16x16x32_bf16 v[14:17], v[172:175], v[226:229], v[14:17]
	v_mfma_f32_16x16x32_bf16 v[10:13], v[180:183], v[226:229], v[10:13]
	s_barrier
	s_setprio 0
	s_add_u32 s40, s40, 0x100
	s_addc_u32 s49, s49, 0
	s_add_u32 s10, s10, 0x100
	s_addc_u32 s11, s11, 0
	s_cmp_ge_u32 vcc_lo, s19
	s_mov_b32 s38, vcc_lo
	s_cbranch_scc0 .LBB0_262
	v_readlane_b32 s10, v254, 27
	v_readlane_b32 s11, v254, 28
	s_and_b64 vcc, exec, s[10:11]
	s_cbranch_vccz .LBB0_270
	s_barrier
	s_cmp_lt_i32 s18, 0
	s_mov_b64 s[10:11], -1
	s_cbranch_scc1 .LBB0_271

.LBB0_1693:
	ds_read_b128 v[128:131], v169
	ds_read_b128 v[132:135], v169 offset:1024
	ds_read_b128 v[136:139], v169 offset:2048
	ds_read_b128 v[140:143], v169 offset:3072
	ds_read_b128 v[158:161], v170
	ds_read_b128 v[162:165], v170 offset:1024
	ds_read_b128 v[172:175], v170 offset:2048
	ds_read_b128 v[176:179], v170 offset:3072
	s_add_u32 s24, s22, 0xfff80080
	s_addc_u32 s25, s23, -1
	s_cmp_eq_u32 s36, 4
	s_cselect_b32 s27, s5, s25
	s_cselect_b32 s26, s4, s24
	s_cselect_b32 s25, s13, s35
	s_cselect_b32 s24, s15, s34
	v_lshl_add_u64 v[212:213], s[22:23], 0, v[152:153]
	s_add_i32 m0, s94, 0xc000
	ds_read_b128 v[180:183], v171
	ds_read_b128 v[184:187], v171 offset:1024
	ds_read_b128 v[188:191], v171 offset:2048
	ds_read_b128 v[192:195], v171 offset:3072
	ds_read_b128 v[196:199], v171 offset:4096
	ds_read_b128 v[200:203], v171 offset:5120
	ds_read_b128 v[204:207], v171 offset:6144
	ds_read_b128 v[208:211], v171 offset:7168
	global_load_lds_dwordx4 v[212:213], off
	v_lshl_add_u64 v[212:213], s[22:23], 0, v[154:155]
	s_add_i32 m0, s94, 0xe000
	s_nop 0
	global_load_lds_dwordx4 v[212:213], off
	s_waitcnt vmcnt(8)
	s_waitcnt lgkmcnt(0)
	.p2alignl 3, 3212836864
	s_setprio 1
	s_barrier
	v_mfma_f32_16x16x32_bf16 v[80:83], v[128:131], v[180:183], v[80:83]
	v_mfma_f32_16x16x32_bf16 v[92:95], v[136:139], v[180:183], v[92:95]
	v_mfma_f32_16x16x32_bf16 v[84:87], v[128:131], v[188:191], v[84:87]
	v_mfma_f32_16x16x32_bf16 v[96:99], v[136:139], v[188:191], v[96:99]
	v_mfma_f32_16x16x32_bf16 v[88:91], v[128:131], v[196:199], v[88:91]
	v_mfma_f32_16x16x32_bf16 v[100:103], v[136:139], v[196:199], v[100:103]
	v_mfma_f32_16x16x32_bf16 v[72:75], v[128:131], v[204:207], v[72:75]
	v_mfma_f32_16x16x32_bf16 v[76:79], v[136:139], v[204:207], v[76:79]
	v_mfma_f32_16x16x32_bf16 v[80:83], v[132:135], v[184:187], v[80:83]
	v_mfma_f32_16x16x32_bf16 v[92:95], v[140:143], v[184:187], v[92:95]
	v_mfma_f32_16x16x32_bf16 v[84:87], v[132:135], v[192:195], v[84:87]
	v_mfma_f32_16x16x32_bf16 v[96:99], v[140:143], v[192:195], v[96:99]
	v_mfma_f32_16x16x32_bf16 v[88:91], v[132:135], v[200:203], v[88:91]
	v_mfma_f32_16x16x32_bf16 v[100:103], v[140:143], v[200:203], v[100:103]
	v_mfma_f32_16x16x32_bf16 v[72:75], v[132:135], v[208:211], v[72:75]
	v_mfma_f32_16x16x32_bf16 v[76:79], v[140:143], v[208:211], v[76:79]
	s_setprio 0
	s_setprio 1
	v_mfma_f32_16x16x32_bf16 v[104:107], v[158:161], v[180:183], v[104:107]
	v_mfma_f32_16x16x32_bf16 v[116:119], v[172:175], v[180:183], v[116:119]
	v_mfma_f32_16x16x32_bf16 v[108:111], v[158:161], v[188:191], v[108:111]
	v_mfma_f32_16x16x32_bf16 v[120:123], v[172:175], v[188:191], v[120:123]
	v_mfma_f32_16x16x32_bf16 v[112:115], v[158:161], v[196:199], v[112:115]
	v_mfma_f32_16x16x32_bf16 v[124:127], v[172:175], v[196:199], v[124:127]
	v_mfma_f32_16x16x32_bf16 v[68:71], v[158:161], v[204:207], v[68:71]
	v_mfma_f32_16x16x32_bf16 v[64:67], v[172:175], v[204:207], v[64:67]
	v_mfma_f32_16x16x32_bf16 v[104:107], v[162:165], v[184:187], v[104:107]
	v_mfma_f32_16x16x32_bf16 v[116:119], v[176:179], v[184:187], v[116:119]
	v_mfma_f32_16x16x32_bf16 v[108:111], v[162:165], v[192:195], v[108:111]
	v_mfma_f32_16x16x32_bf16 v[120:123], v[176:179], v[192:195], v[120:123]
	v_mfma_f32_16x16x32_bf16 v[112:115], v[162:165], v[200:203], v[112:115]
	v_mfma_f32_16x16x32_bf16 v[124:127], v[176:179], v[200:203], v[124:127]
	v_mfma_f32_16x16x32_bf16 v[68:71], v[162:165], v[208:211], v[68:71]
	v_mfma_f32_16x16x32_bf16 v[64:67], v[176:179], v[208:211], v[64:67]
	s_barrier
	s_setprio 0
	s_add_i32 s37, s31, s97
	v_lshl_add_u64 v[212:213], s[24:25], 0, v[148:149]
	s_mov_b32 m0, s37
	ds_read_b128 v[180:183], v171 offset:16384
	ds_read_b128 v[184:187], v171 offset:17408
	ds_read_b128 v[188:191], v171 offset:18432
	ds_read_b128 v[192:195], v171 offset:19456
	ds_read_b128 v[196:199], v171 offset:20480
	ds_read_b128 v[200:203], v171 offset:21504
	ds_read_b128 v[204:207], v171 offset:22528
	ds_read_b128 v[208:211], v171 offset:23552
	global_load_lds_dwordx4 v[212:213], off
	s_add_i32 m0, s37, 0x2000
	s_add_u32 s38, s24, 0x20000
	v_lshl_add_u64 v[214:215], s[24:25], 0, v[144:145]
	s_addc_u32 s39, s25, 0
	s_add_i32 s37, s33, s97
	global_load_lds_dwordx4 v[214:215], off
	v_lshl_add_u64 v[216:217], s[38:39], 0, v[148:149]
	s_mov_b32 m0, s37
	v_lshl_add_u64 v[218:219], s[26:27], 0, v[146:147]
	global_load_lds_dwordx4 v[216:217], off
	v_lshl_add_u64 v[216:217], s[38:39], 0, v[144:145]
	s_add_i32 m0, s37, 0x2000
	s_nop 0
	global_load_lds_dwordx4 v[216:217], off
	v_lshl_add_u64 v[216:217], s[26:27], 0, v[150:151]
	s_mov_b32 m0, s94
	s_nop 0
	global_load_lds_dwordx4 v[216:217], off
	s_mov_b32 m0, s3
	s_nop 0
	global_load_lds_dwordx4 v[218:219], off
	s_waitcnt vmcnt(8)
	s_waitcnt lgkmcnt(0)
	.p2alignl 3, 3212836864
	s_setprio 1
	s_barrier
	v_mfma_f32_16x16x32_bf16 v[48:51], v[128:131], v[180:183], v[48:51]
	v_mfma_f32_16x16x32_bf16 v[52:55], v[136:139], v[180:183], v[52:55]
	v_mfma_f32_16x16x32_bf16 v[32:35], v[128:131], v[188:191], v[32:35]
	v_mfma_f32_16x16x32_bf16 v[36:39], v[136:139], v[188:191], v[36:39]
	v_mfma_f32_16x16x32_bf16 v[16:19], v[128:131], v[196:199], v[16:19]
	v_mfma_f32_16x16x32_bf16 v[20:23], v[136:139], v[196:199], v[20:23]
	v_mfma_f32_16x16x32_bf16 v[0:3], v[128:131], v[204:207], v[0:3]
	v_mfma_f32_16x16x32_bf16 v[4:7], v[136:139], v[204:207], v[4:7]
	v_mfma_f32_16x16x32_bf16 v[48:51], v[132:135], v[184:187], v[48:51]
	v_mfma_f32_16x16x32_bf16 v[52:55], v[140:143], v[184:187], v[52:55]
	v_mfma_f32_16x16x32_bf16 v[32:35], v[132:135], v[192:195], v[32:35]
	v_mfma_f32_16x16x32_bf16 v[36:39], v[140:143], v[192:195], v[36:39]
	v_mfma_f32_16x16x32_bf16 v[16:19], v[132:135], v[200:203], v[16:19]
	v_mfma_f32_16x16x32_bf16 v[20:23], v[140:143], v[200:203], v[20:23]
	v_mfma_f32_16x16x32_bf16 v[0:3], v[132:135], v[208:211], v[0:3]
	v_mfma_f32_16x16x32_bf16 v[4:7], v[140:143], v[208:211], v[4:7]
	s_setprio 0
	s_setprio 1
	v_mfma_f32_16x16x32_bf16 v[56:59], v[158:161], v[180:183], v[56:59]
	v_mfma_f32_16x16x32_bf16 v[60:63], v[172:175], v[180:183], v[60:63]
	v_mfma_f32_16x16x32_bf16 v[40:43], v[158:161], v[188:191], v[40:43]
	v_mfma_f32_16x16x32_bf16 v[44:47], v[172:175], v[188:191], v[44:47]
	v_mfma_f32_16x16x32_bf16 v[24:27], v[158:161], v[196:199], v[24:27]
	v_mfma_f32_16x16x32_bf16 v[28:31], v[172:175], v[196:199], v[28:31]
	v_mfma_f32_16x16x32_bf16 v[8:11], v[158:161], v[204:207], v[8:11]
	v_mfma_f32_16x16x32_bf16 v[12:15], v[172:175], v[204:207], v[12:15]
	v_mfma_f32_16x16x32_bf16 v[56:59], v[162:165], v[184:187], v[56:59]
	v_mfma_f32_16x16x32_bf16 v[60:63], v[176:179], v[184:187], v[60:63]
	v_mfma_f32_16x16x32_bf16 v[40:43], v[162:165], v[192:195], v[40:43]
	v_mfma_f32_16x16x32_bf16 v[44:47], v[176:179], v[192:195], v[44:47]
	v_mfma_f32_16x16x32_bf16 v[24:27], v[162:165], v[200:203], v[24:27]
	v_mfma_f32_16x16x32_bf16 v[28:31], v[176:179], v[200:203], v[28:31]
	v_mfma_f32_16x16x32_bf16 v[8:11], v[162:165], v[208:211], v[8:11]
	v_mfma_f32_16x16x32_bf16 v[12:15], v[176:179], v[208:211], v[12:15]
	s_barrier
	s_setprio 0
	s_add_i32 s37, 0, 0x18000
	s_add_i32 s38, 0, 0x1c000
	v_add_u32_e32 v140, s37, v167
	v_add_u32_e32 v176, s38, v167
	ds_read_b128 v[128:131], v140
	ds_read_b128 v[132:135], v140 offset:1024
	ds_read_b128 v[136:139], v140 offset:2048
	ds_read_b128 v[140:143], v140 offset:3072
	ds_read_b128 v[158:161], v176
	ds_read_b128 v[162:165], v176 offset:1024
	ds_read_b128 v[172:175], v176 offset:2048
	ds_read_b128 v[176:179], v176 offset:3072
	s_add_u32 s26, s26, 0x80000
	s_addc_u32 s27, s27, 0
	s_mov_b32 m0, s7
	v_lshl_add_u64 v[220:221], s[26:27], 0, v[150:151]
	ds_read_b128 v[180:183], v171 offset:32768
	ds_read_b128 v[184:187], v171 offset:33792
	ds_read_b128 v[188:191], v171 offset:34816
	ds_read_b128 v[192:195], v171 offset:35840
	ds_read_b128 v[196:199], v171 offset:36864
	ds_read_b128 v[200:203], v171 offset:37888
	ds_read_b128 v[204:207], v171 offset:38912
	ds_read_b128 v[208:211], v171 offset:39936
	global_load_lds_dwordx4 v[220:221], off
	v_lshl_add_u64 v[220:221], s[26:27], 0, v[146:147]
	s_mov_b32 m0, s19
	s_nop 0
	global_load_lds_dwordx4 v[220:221], off
	s_waitcnt vmcnt(8)
	s_waitcnt lgkmcnt(0)
	.p2alignl 3, 3212836864
	s_setprio 1
	s_barrier
	v_mfma_f32_16x16x32_bf16 v[80:83], v[128:131], v[180:183], v[80:83]
	v_mfma_f32_16x16x32_bf16 v[92:95], v[136:139], v[180:183], v[92:95]
	v_mfma_f32_16x16x32_bf16 v[84:87], v[128:131], v[188:191], v[84:87]
	v_mfma_f32_16x16x32_bf16 v[96:99], v[136:139], v[188:191], v[96:99]
	v_mfma_f32_16x16x32_bf16 v[88:91], v[128:131], v[196:199], v[88:91]
	v_mfma_f32_16x16x32_bf16 v[100:103], v[136:139], v[196:199], v[100:103]
	v_mfma_f32_16x16x32_bf16 v[72:75], v[128:131], v[204:207], v[72:75]
	v_mfma_f32_16x16x32_bf16 v[76:79], v[136:139], v[204:207], v[76:79]
	v_mfma_f32_16x16x32_bf16 v[80:83], v[132:135], v[184:187], v[80:83]
	v_mfma_f32_16x16x32_bf16 v[92:95], v[140:143], v[184:187], v[92:95]
	v_mfma_f32_16x16x32_bf16 v[84:87], v[132:135], v[192:195], v[84:87]
	v_mfma_f32_16x16x32_bf16 v[96:99], v[140:143], v[192:195], v[96:99]
	v_mfma_f32_16x16x32_bf16 v[88:91], v[132:135], v[200:203], v[88:91]
	v_mfma_f32_16x16x32_bf16 v[100:103], v[140:143], v[200:203], v[100:103]
	v_mfma_f32_16x16x32_bf16 v[72:75], v[132:135], v[208:211], v[72:75]
	v_mfma_f32_16x16x32_bf16 v[76:79], v[140:143], v[208:211], v[76:79]
	s_setprio 0
	s_setprio 1
	v_mfma_f32_16x16x32_bf16 v[104:107], v[158:161], v[180:183], v[104:107]
	v_mfma_f32_16x16x32_bf16 v[116:119], v[172:175], v[180:183], v[116:119]
	v_mfma_f32_16x16x32_bf16 v[108:111], v[158:161], v[188:191], v[108:111]
	v_mfma_f32_16x16x32_bf16 v[120:123], v[172:175], v[188:191], v[120:123]
	v_mfma_f32_16x16x32_bf16 v[112:115], v[158:161], v[196:199], v[112:115]
	v_mfma_f32_16x16x32_bf16 v[124:127], v[172:175], v[196:199], v[124:127]
	v_mfma_f32_16x16x32_bf16 v[68:71], v[158:161], v[204:207], v[68:71]
	v_mfma_f32_16x16x32_bf16 v[64:67], v[172:175], v[204:207], v[64:67]
	v_mfma_f32_16x16x32_bf16 v[104:107], v[162:165], v[184:187], v[104:107]
	v_mfma_f32_16x16x32_bf16 v[116:119], v[176:179], v[184:187], v[116:119]
	v_mfma_f32_16x16x32_bf16 v[108:111], v[162:165], v[192:195], v[108:111]
	v_mfma_f32_16x16x32_bf16 v[120:123], v[176:179], v[192:195], v[120:123]
	v_mfma_f32_16x16x32_bf16 v[112:115], v[162:165], v[200:203], v[112:115]
	v_mfma_f32_16x16x32_bf16 v[124:127], v[176:179], v[200:203], v[124:127]
	v_mfma_f32_16x16x32_bf16 v[68:71], v[162:165], v[208:211], v[68:71]
	v_mfma_f32_16x16x32_bf16 v[64:67], v[176:179], v[208:211], v[64:67]
	s_barrier
	s_setprio 0
	s_add_i32 s26, s37, s97
	v_lshl_add_u64 v[212:213], v[212:213], 0, s[0:1]
	s_mov_b32 m0, s26
	ds_read_b128 v[180:183], v171 offset:49152
	ds_read_b128 v[184:187], v171 offset:50176
	ds_read_b128 v[188:191], v171 offset:51200
	ds_read_b128 v[192:195], v171 offset:52224
	ds_read_b128 v[196:199], v171 offset:53248
	ds_read_b128 v[200:203], v171 offset:54272
	ds_read_b128 v[204:207], v171 offset:55296
	ds_read_b128 v[208:211], v171 offset:56320
	global_load_lds_dwordx4 v[212:213], off
	s_add_i32 m0, s26, 0x2000
	s_add_u32 s24, s24, 0x20080
	v_lshl_add_u64 v[212:213], v[214:215], 0, s[0:1]
	s_addc_u32 s25, s25, 0
	s_add_i32 s26, s38, s97
	global_load_lds_dwordx4 v[212:213], off
	v_lshl_add_u64 v[212:213], s[24:25], 0, v[148:149]
	s_mov_b32 m0, s26
	s_nop 0
	global_load_lds_dwordx4 v[212:213], off
	v_lshl_add_u64 v[212:213], s[24:25], 0, v[144:145]
	s_add_i32 m0, s26, 0x2000
	s_nop 0
	global_load_lds_dwordx4 v[212:213], off
	v_lshl_add_u64 v[212:213], v[216:217], 0, s[0:1]
	s_mov_b32 m0, s28
	s_nop 0
	global_load_lds_dwordx4 v[212:213], off
	v_lshl_add_u64 v[212:213], v[218:219], 0, s[0:1]
	s_mov_b32 m0, s29
	s_nop 0
	global_load_lds_dwordx4 v[212:213], off
	s_waitcnt vmcnt(8)
	s_waitcnt lgkmcnt(0)
	.p2alignl 3, 3212836864
	s_setprio 1
	s_barrier
	v_mfma_f32_16x16x32_bf16 v[48:51], v[128:131], v[180:183], v[48:51]
	v_mfma_f32_16x16x32_bf16 v[52:55], v[136:139], v[180:183], v[52:55]
	v_mfma_f32_16x16x32_bf16 v[32:35], v[128:131], v[188:191], v[32:35]
	v_mfma_f32_16x16x32_bf16 v[36:39], v[136:139], v[188:191], v[36:39]
	v_mfma_f32_16x16x32_bf16 v[16:19], v[128:131], v[196:199], v[16:19]
	v_mfma_f32_16x16x32_bf16 v[20:23], v[136:139], v[196:199], v[20:23]
	v_mfma_f32_16x16x32_bf16 v[0:3], v[128:131], v[204:207], v[0:3]
	v_mfma_f32_16x16x32_bf16 v[4:7], v[136:139], v[204:207], v[4:7]
	v_mfma_f32_16x16x32_bf16 v[48:51], v[132:135], v[184:187], v[48:51]
	v_mfma_f32_16x16x32_bf16 v[52:55], v[140:143], v[184:187], v[52:55]
	v_mfma_f32_16x16x32_bf16 v[32:35], v[132:135], v[192:195], v[32:35]
	v_mfma_f32_16x16x32_bf16 v[36:39], v[140:143], v[192:195], v[36:39]
	v_mfma_f32_16x16x32_bf16 v[16:19], v[132:135], v[200:203], v[16:19]
	v_mfma_f32_16x16x32_bf16 v[20:23], v[140:143], v[200:203], v[20:23]
	v_mfma_f32_16x16x32_bf16 v[0:3], v[132:135], v[208:211], v[0:3]
	v_mfma_f32_16x16x32_bf16 v[4:7], v[140:143], v[208:211], v[4:7]
	s_setprio 0
	s_setprio 1
	v_mfma_f32_16x16x32_bf16 v[56:59], v[158:161], v[180:183], v[56:59]
	v_mfma_f32_16x16x32_bf16 v[60:63], v[172:175], v[180:183], v[60:63]
	v_mfma_f32_16x16x32_bf16 v[40:43], v[158:161], v[188:191], v[40:43]
	v_mfma_f32_16x16x32_bf16 v[44:47], v[172:175], v[188:191], v[44:47]
	v_mfma_f32_16x16x32_bf16 v[24:27], v[158:161], v[196:199], v[24:27]
	v_mfma_f32_16x16x32_bf16 v[28:31], v[172:175], v[196:199], v[28:31]
	v_mfma_f32_16x16x32_bf16 v[8:11], v[158:161], v[204:207], v[8:11]
	v_mfma_f32_16x16x32_bf16 v[12:15], v[172:175], v[204:207], v[12:15]
	v_mfma_f32_16x16x32_bf16 v[56:59], v[162:165], v[184:187], v[56:59]
	v_mfma_f32_16x16x32_bf16 v[60:63], v[176:179], v[184:187], v[60:63]
	v_mfma_f32_16x16x32_bf16 v[40:43], v[162:165], v[192:195], v[40:43]
	v_mfma_f32_16x16x32_bf16 v[44:47], v[176:179], v[192:195], v[44:47]
	v_mfma_f32_16x16x32_bf16 v[24:27], v[162:165], v[200:203], v[24:27]
	v_mfma_f32_16x16x32_bf16 v[28:31], v[176:179], v[200:203], v[28:31]
	v_mfma_f32_16x16x32_bf16 v[8:11], v[162:165], v[208:211], v[8:11]
	v_mfma_f32_16x16x32_bf16 v[12:15], v[176:179], v[208:211], v[12:15]
	s_barrier
	s_setprio 0
	s_add_i32 s36, s36, 2
	s_add_u32 s34, s34, 0x100
	s_addc_u32 s35, s35, 0
	s_add_u32 s22, s22, 0x100
	s_addc_u32 s23, s23, 0
	s_cmp_gt_u32 s36, 5
	s_cbranch_scc0 .LBB0_1693
	v_readlane_b32 s22, v254, 27
	v_readlane_b32 s23, v254, 28
	s_and_b64 vcc, exec, s[22:23]
	s_cbranch_vccz .LBB0_1696
	s_barrier

.LBB0_2020:
	ds_read_b128 v[128:131], v244
	ds_read_b128 v[132:135], v244 offset:1024
	ds_read_b128 v[136:139], v244 offset:2048
	ds_read_b128 v[140:143], v244 offset:3072
	ds_read_b128 v[144:147], v245
	ds_read_b128 v[148:151], v245 offset:1024
	ds_read_b128 v[152:155], v245 offset:2048
	ds_read_b128 v[156:159], v245 offset:3072
	s_add_i32 s71, s46, 2
	s_add_u32 s47, s44, 0xfff00080
	s_addc_u32 s48, s45, -1
	s_cmp_eq_u32 s68, s46
	s_cselect_b32 s46, s43, s69
	s_cselect_b32 s49, s5, s48
	s_cselect_b32 s48, s23, s47
	s_cselect_b32 s47, s21, s70
	v_lshl_add_u64 v[192:193], s[44:45], 0, v[218:219]
	s_add_i32 m0, s94, 0xc000
	ds_read_b128 v[160:163], v246
	ds_read_b128 v[164:167], v246 offset:1024
	ds_read_b128 v[168:171], v246 offset:2048
	ds_read_b128 v[172:175], v246 offset:3072
	ds_read_b128 v[176:179], v246 offset:4096
	ds_read_b128 v[180:183], v246 offset:5120
	ds_read_b128 v[184:187], v246 offset:6144
	ds_read_b128 v[188:191], v246 offset:7168
	global_load_lds_dwordx4 v[192:193], off
	v_lshl_add_u64 v[192:193], s[44:45], 0, v[220:221]
	s_add_i32 m0, s94, 0xe000
	s_nop 0
	global_load_lds_dwordx4 v[192:193], off
	s_waitcnt vmcnt(8)
	s_waitcnt lgkmcnt(0)
	.p2alignl 3, 3212836864
	s_setprio 1
	s_barrier
	v_mfma_f32_16x16x32_bf16 v[112:115], v[128:131], v[160:163], v[112:115]
	v_mfma_f32_16x16x32_bf16 v[116:119], v[136:139], v[160:163], v[116:119]
	v_mfma_f32_16x16x32_bf16 v[100:103], v[128:131], v[168:171], v[100:103]
	v_mfma_f32_16x16x32_bf16 v[96:99], v[136:139], v[168:171], v[96:99]
	v_mfma_f32_16x16x32_bf16 v[84:87], v[128:131], v[176:179], v[84:87]
	v_mfma_f32_16x16x32_bf16 v[80:83], v[136:139], v[176:179], v[80:83]
	v_mfma_f32_16x16x32_bf16 v[52:55], v[128:131], v[184:187], v[52:55]
	v_mfma_f32_16x16x32_bf16 v[48:51], v[136:139], v[184:187], v[48:51]
	v_mfma_f32_16x16x32_bf16 v[112:115], v[132:135], v[164:167], v[112:115]
	v_mfma_f32_16x16x32_bf16 v[116:119], v[140:143], v[164:167], v[116:119]
	v_mfma_f32_16x16x32_bf16 v[100:103], v[132:135], v[172:175], v[100:103]
	v_mfma_f32_16x16x32_bf16 v[96:99], v[140:143], v[172:175], v[96:99]
	v_mfma_f32_16x16x32_bf16 v[84:87], v[132:135], v[180:183], v[84:87]
	v_mfma_f32_16x16x32_bf16 v[80:83], v[140:143], v[180:183], v[80:83]
	v_mfma_f32_16x16x32_bf16 v[52:55], v[132:135], v[188:191], v[52:55]
	v_mfma_f32_16x16x32_bf16 v[48:51], v[140:143], v[188:191], v[48:51]
	s_setprio 0
	s_setprio 1
	v_mfma_f32_16x16x32_bf16 v[124:127], v[144:147], v[160:163], v[124:127]
	v_mfma_f32_16x16x32_bf16 v[120:123], v[152:155], v[160:163], v[120:123]
	v_mfma_f32_16x16x32_bf16 v[108:111], v[144:147], v[168:171], v[108:111]
	v_mfma_f32_16x16x32_bf16 v[104:107], v[152:155], v[168:171], v[104:107]
	v_mfma_f32_16x16x32_bf16 v[92:95], v[144:147], v[176:179], v[92:95]
	v_mfma_f32_16x16x32_bf16 v[88:91], v[152:155], v[176:179], v[88:91]
	v_mfma_f32_16x16x32_bf16 v[68:71], v[144:147], v[184:187], v[68:71]
	v_mfma_f32_16x16x32_bf16 v[64:67], v[152:155], v[184:187], v[64:67]
	v_mfma_f32_16x16x32_bf16 v[124:127], v[148:151], v[164:167], v[124:127]
	v_mfma_f32_16x16x32_bf16 v[120:123], v[156:159], v[164:167], v[120:123]
	v_mfma_f32_16x16x32_bf16 v[108:111], v[148:151], v[172:175], v[108:111]
	v_mfma_f32_16x16x32_bf16 v[104:107], v[156:159], v[172:175], v[104:107]
	v_mfma_f32_16x16x32_bf16 v[92:95], v[148:151], v[180:183], v[92:95]
	v_mfma_f32_16x16x32_bf16 v[88:91], v[156:159], v[180:183], v[88:91]
	v_mfma_f32_16x16x32_bf16 v[68:71], v[148:151], v[188:191], v[68:71]
	v_mfma_f32_16x16x32_bf16 v[64:67], v[156:159], v[188:191], v[64:67]
	s_barrier
	s_setprio 0
	s_add_i32 s76, s60, s97
	v_lshl_add_u64 v[192:193], s[46:47], 0, v[210:211]
	s_mov_b32 m0, s76
	ds_read_b128 v[160:163], v246 offset:16384
	ds_read_b128 v[164:167], v246 offset:17408
	ds_read_b128 v[168:171], v246 offset:18432
	ds_read_b128 v[172:175], v246 offset:19456
	ds_read_b128 v[176:179], v246 offset:20480
	ds_read_b128 v[180:183], v246 offset:21504
	ds_read_b128 v[184:187], v246 offset:22528
	ds_read_b128 v[188:191], v246 offset:23552
	global_load_lds_dwordx4 v[192:193], off
	s_add_i32 m0, s76, 0x2000
	s_add_u32 s76, s46, 0x100000
	v_lshl_add_u64 v[194:195], s[46:47], 0, v[214:215]
	s_addc_u32 s77, s47, 0
	s_add_i32 s78, s61, s97
	global_load_lds_dwordx4 v[194:195], off
	v_lshl_add_u64 v[196:197], s[76:77], 0, v[210:211]
	s_mov_b32 m0, s78
	v_lshl_add_u64 v[198:199], s[48:49], 0, v[212:213]
	global_load_lds_dwordx4 v[196:197], off
	v_lshl_add_u64 v[196:197], s[76:77], 0, v[214:215]
	s_add_i32 m0, s78, 0x2000
	s_nop 0
	global_load_lds_dwordx4 v[196:197], off
	v_lshl_add_u64 v[196:197], s[48:49], 0, v[208:209]
	s_mov_b32 m0, s94
	s_nop 0
	global_load_lds_dwordx4 v[196:197], off
	s_mov_b32 m0, s2
	s_nop 0
	global_load_lds_dwordx4 v[198:199], off
	s_waitcnt vmcnt(8)
	s_waitcnt lgkmcnt(0)
	.p2alignl 3, 3212836864
	s_setprio 1
	s_barrier
	v_mfma_f32_16x16x32_bf16 v[60:63], v[128:131], v[160:163], v[60:63]
	v_mfma_f32_16x16x32_bf16 v[56:59], v[136:139], v[160:163], v[56:59]
	v_mfma_f32_16x16x32_bf16 v[36:39], v[128:131], v[168:171], v[36:39]
	v_mfma_f32_16x16x32_bf16 v[32:35], v[136:139], v[168:171], v[32:35]
	v_mfma_f32_16x16x32_bf16 v[20:23], v[128:131], v[176:179], v[20:23]
	v_mfma_f32_16x16x32_bf16 v[16:19], v[136:139], v[176:179], v[16:19]
	v_mfma_f32_16x16x32_bf16 v[4:7], v[128:131], v[184:187], v[4:7]
	v_mfma_f32_16x16x32_bf16 v[0:3], v[136:139], v[184:187], v[0:3]
	v_mfma_f32_16x16x32_bf16 v[60:63], v[132:135], v[164:167], v[60:63]
	v_mfma_f32_16x16x32_bf16 v[56:59], v[140:143], v[164:167], v[56:59]
	v_mfma_f32_16x16x32_bf16 v[36:39], v[132:135], v[172:175], v[36:39]
	v_mfma_f32_16x16x32_bf16 v[32:35], v[140:143], v[172:175], v[32:35]
	v_mfma_f32_16x16x32_bf16 v[20:23], v[132:135], v[180:183], v[20:23]
	v_mfma_f32_16x16x32_bf16 v[16:19], v[140:143], v[180:183], v[16:19]
	v_mfma_f32_16x16x32_bf16 v[4:7], v[132:135], v[188:191], v[4:7]
	v_mfma_f32_16x16x32_bf16 v[0:3], v[140:143], v[188:191], v[0:3]
	s_setprio 0
	s_setprio 1
	v_mfma_f32_16x16x32_bf16 v[76:79], v[144:147], v[160:163], v[76:79]
	v_mfma_f32_16x16x32_bf16 v[72:75], v[152:155], v[160:163], v[72:75]
	v_mfma_f32_16x16x32_bf16 v[44:47], v[144:147], v[168:171], v[44:47]
	v_mfma_f32_16x16x32_bf16 v[40:43], v[152:155], v[168:171], v[40:43]
	v_mfma_f32_16x16x32_bf16 v[28:31], v[144:147], v[176:179], v[28:31]
	v_mfma_f32_16x16x32_bf16 v[24:27], v[152:155], v[176:179], v[24:27]
	v_mfma_f32_16x16x32_bf16 v[12:15], v[144:147], v[184:187], v[12:15]
	v_mfma_f32_16x16x32_bf16 v[8:11], v[152:155], v[184:187], v[8:11]
	v_mfma_f32_16x16x32_bf16 v[76:79], v[148:151], v[164:167], v[76:79]
	v_mfma_f32_16x16x32_bf16 v[72:75], v[156:159], v[164:167], v[72:75]
	v_mfma_f32_16x16x32_bf16 v[44:47], v[148:151], v[172:175], v[44:47]
	v_mfma_f32_16x16x32_bf16 v[40:43], v[156:159], v[172:175], v[40:43]
	v_mfma_f32_16x16x32_bf16 v[28:31], v[148:151], v[180:183], v[28:31]
	v_mfma_f32_16x16x32_bf16 v[24:27], v[156:159], v[180:183], v[24:27]
	v_mfma_f32_16x16x32_bf16 v[12:15], v[148:151], v[188:191], v[12:15]
	v_mfma_f32_16x16x32_bf16 v[8:11], v[156:159], v[188:191], v[8:11]
	s_barrier
	s_setprio 0
	s_add_i32 s76, 0, 0x18000
	s_add_i32 s77, 0, 0x1c000
	v_add_u32_e32 v140, s76, v243
	v_add_u32_e32 v156, s77, v243
	ds_read_b128 v[128:131], v140
	ds_read_b128 v[132:135], v140 offset:1024
	ds_read_b128 v[136:139], v140 offset:2048
	ds_read_b128 v[140:143], v140 offset:3072
	ds_read_b128 v[144:147], v156
	ds_read_b128 v[148:151], v156 offset:1024
	ds_read_b128 v[152:155], v156 offset:2048
	ds_read_b128 v[156:159], v156 offset:3072
	s_add_u32 s48, s48, 0x100000
	s_addc_u32 s49, s49, 0
	s_mov_b32 m0, s3
	v_lshl_add_u64 v[200:201], s[48:49], 0, v[208:209]
	ds_read_b128 v[160:163], v246 offset:32768
	ds_read_b128 v[164:167], v246 offset:33792
	ds_read_b128 v[168:171], v246 offset:34816
	ds_read_b128 v[172:175], v246 offset:35840
	ds_read_b128 v[176:179], v246 offset:36864
	ds_read_b128 v[180:183], v246 offset:37888
	ds_read_b128 v[184:187], v246 offset:38912
	ds_read_b128 v[188:191], v246 offset:39936
	global_load_lds_dwordx4 v[200:201], off
	v_lshl_add_u64 v[200:201], s[48:49], 0, v[212:213]
	s_mov_b32 m0, s33
	s_nop 0
	global_load_lds_dwordx4 v[200:201], off
	s_waitcnt vmcnt(8)
	s_waitcnt lgkmcnt(0)
	.p2alignl 3, 3212836864
	s_setprio 1
	s_barrier
	v_mfma_f32_16x16x32_bf16 v[112:115], v[128:131], v[160:163], v[112:115]
	v_mfma_f32_16x16x32_bf16 v[116:119], v[136:139], v[160:163], v[116:119]
	v_mfma_f32_16x16x32_bf16 v[100:103], v[128:131], v[168:171], v[100:103]
	v_mfma_f32_16x16x32_bf16 v[96:99], v[136:139], v[168:171], v[96:99]
	v_mfma_f32_16x16x32_bf16 v[84:87], v[128:131], v[176:179], v[84:87]
	v_mfma_f32_16x16x32_bf16 v[80:83], v[136:139], v[176:179], v[80:83]
	v_mfma_f32_16x16x32_bf16 v[52:55], v[128:131], v[184:187], v[52:55]
	v_mfma_f32_16x16x32_bf16 v[48:51], v[136:139], v[184:187], v[48:51]
	v_mfma_f32_16x16x32_bf16 v[112:115], v[132:135], v[164:167], v[112:115]
	v_mfma_f32_16x16x32_bf16 v[116:119], v[140:143], v[164:167], v[116:119]
	v_mfma_f32_16x16x32_bf16 v[100:103], v[132:135], v[172:175], v[100:103]
	v_mfma_f32_16x16x32_bf16 v[96:99], v[140:143], v[172:175], v[96:99]
	v_mfma_f32_16x16x32_bf16 v[84:87], v[132:135], v[180:183], v[84:87]
	v_mfma_f32_16x16x32_bf16 v[80:83], v[140:143], v[180:183], v[80:83]
	v_mfma_f32_16x16x32_bf16 v[52:55], v[132:135], v[188:191], v[52:55]
	v_mfma_f32_16x16x32_bf16 v[48:51], v[140:143], v[188:191], v[48:51]
	s_setprio 0
	s_setprio 1
	v_mfma_f32_16x16x32_bf16 v[124:127], v[144:147], v[160:163], v[124:127]
	v_mfma_f32_16x16x32_bf16 v[120:123], v[152:155], v[160:163], v[120:123]
	v_mfma_f32_16x16x32_bf16 v[108:111], v[144:147], v[168:171], v[108:111]
	v_mfma_f32_16x16x32_bf16 v[104:107], v[152:155], v[168:171], v[104:107]
	v_mfma_f32_16x16x32_bf16 v[92:95], v[144:147], v[176:179], v[92:95]
	v_mfma_f32_16x16x32_bf16 v[88:91], v[152:155], v[176:179], v[88:91]
	v_mfma_f32_16x16x32_bf16 v[68:71], v[144:147], v[184:187], v[68:71]
	v_mfma_f32_16x16x32_bf16 v[64:67], v[152:155], v[184:187], v[64:67]
	v_mfma_f32_16x16x32_bf16 v[124:127], v[148:151], v[164:167], v[124:127]
	v_mfma_f32_16x16x32_bf16 v[120:123], v[156:159], v[164:167], v[120:123]
	v_mfma_f32_16x16x32_bf16 v[108:111], v[148:151], v[172:175], v[108:111]
	v_mfma_f32_16x16x32_bf16 v[104:107], v[156:159], v[172:175], v[104:107]
	v_mfma_f32_16x16x32_bf16 v[92:95], v[148:151], v[180:183], v[92:95]
	v_mfma_f32_16x16x32_bf16 v[88:91], v[156:159], v[180:183], v[88:91]
	v_mfma_f32_16x16x32_bf16 v[68:71], v[148:151], v[188:191], v[68:71]
	v_mfma_f32_16x16x32_bf16 v[64:67], v[156:159], v[188:191], v[64:67]
	s_barrier
	s_setprio 0
	s_add_i32 s48, s76, s97
	v_lshl_add_u64 v[192:193], v[192:193], 0, s[16:17]
	s_mov_b32 m0, s48
	ds_read_b128 v[160:163], v246 offset:49152
	ds_read_b128 v[164:167], v246 offset:50176
	ds_read_b128 v[168:171], v246 offset:51200
	ds_read_b128 v[172:175], v246 offset:52224
	ds_read_b128 v[176:179], v246 offset:53248
	ds_read_b128 v[180:183], v246 offset:54272
	ds_read_b128 v[184:187], v246 offset:55296
	ds_read_b128 v[188:191], v246 offset:56320
	global_load_lds_dwordx4 v[192:193], off
	s_add_i32 m0, s48, 0x2000
	s_add_u32 s46, s46, 0x100080
	v_lshl_add_u64 v[192:193], v[194:195], 0, s[16:17]
	s_addc_u32 s47, s47, 0
	s_add_i32 s48, s77, s97
	global_load_lds_dwordx4 v[192:193], off
	v_lshl_add_u64 v[192:193], s[46:47], 0, v[210:211]
	s_mov_b32 m0, s48
	s_nop 0
	global_load_lds_dwordx4 v[192:193], off
	v_lshl_add_u64 v[192:193], s[46:47], 0, v[214:215]
	s_add_i32 m0, s48, 0x2000
	s_nop 0
	global_load_lds_dwordx4 v[192:193], off
	v_lshl_add_u64 v[192:193], v[196:197], 0, s[16:17]
	s_mov_b32 m0, s54
	s_nop 0
	global_load_lds_dwordx4 v[192:193], off
	v_lshl_add_u64 v[192:193], v[198:199], 0, s[16:17]
	s_mov_b32 m0, s55
	s_nop 0
	global_load_lds_dwordx4 v[192:193], off
	s_waitcnt vmcnt(8)
	s_waitcnt lgkmcnt(0)
	.p2alignl 3, 3212836864
	s_setprio 1
	s_barrier
	v_mfma_f32_16x16x32_bf16 v[60:63], v[128:131], v[160:163], v[60:63]
	v_mfma_f32_16x16x32_bf16 v[56:59], v[136:139], v[160:163], v[56:59]
	v_mfma_f32_16x16x32_bf16 v[36:39], v[128:131], v[168:171], v[36:39]
	v_mfma_f32_16x16x32_bf16 v[32:35], v[136:139], v[168:171], v[32:35]
	v_mfma_f32_16x16x32_bf16 v[20:23], v[128:131], v[176:179], v[20:23]
	v_mfma_f32_16x16x32_bf16 v[16:19], v[136:139], v[176:179], v[16:19]
	v_mfma_f32_16x16x32_bf16 v[4:7], v[128:131], v[184:187], v[4:7]
	v_mfma_f32_16x16x32_bf16 v[0:3], v[136:139], v[184:187], v[0:3]
	v_mfma_f32_16x16x32_bf16 v[60:63], v[132:135], v[164:167], v[60:63]
	v_mfma_f32_16x16x32_bf16 v[56:59], v[140:143], v[164:167], v[56:59]
	v_mfma_f32_16x16x32_bf16 v[36:39], v[132:135], v[172:175], v[36:39]
	v_mfma_f32_16x16x32_bf16 v[32:35], v[140:143], v[172:175], v[32:35]
	v_mfma_f32_16x16x32_bf16 v[20:23], v[132:135], v[180:183], v[20:23]
	v_mfma_f32_16x16x32_bf16 v[16:19], v[140:143], v[180:183], v[16:19]
	v_mfma_f32_16x16x32_bf16 v[4:7], v[132:135], v[188:191], v[4:7]
	v_mfma_f32_16x16x32_bf16 v[0:3], v[140:143], v[188:191], v[0:3]
	s_setprio 0
	s_setprio 1
	v_mfma_f32_16x16x32_bf16 v[76:79], v[144:147], v[160:163], v[76:79]
	v_mfma_f32_16x16x32_bf16 v[72:75], v[152:155], v[160:163], v[72:75]
	v_mfma_f32_16x16x32_bf16 v[44:47], v[144:147], v[168:171], v[44:47]
	v_mfma_f32_16x16x32_bf16 v[40:43], v[152:155], v[168:171], v[40:43]
	v_mfma_f32_16x16x32_bf16 v[28:31], v[144:147], v[176:179], v[28:31]
	v_mfma_f32_16x16x32_bf16 v[24:27], v[152:155], v[176:179], v[24:27]
	v_mfma_f32_16x16x32_bf16 v[12:15], v[144:147], v[184:187], v[12:15]
	v_mfma_f32_16x16x32_bf16 v[8:11], v[152:155], v[184:187], v[8:11]
	v_mfma_f32_16x16x32_bf16 v[76:79], v[148:151], v[164:167], v[76:79]
	v_mfma_f32_16x16x32_bf16 v[72:75], v[156:159], v[164:167], v[72:75]
	v_mfma_f32_16x16x32_bf16 v[44:47], v[148:151], v[172:175], v[44:47]
	v_mfma_f32_16x16x32_bf16 v[40:43], v[156:159], v[172:175], v[40:43]
	v_mfma_f32_16x16x32_bf16 v[28:31], v[148:151], v[180:183], v[28:31]
	v_mfma_f32_16x16x32_bf16 v[24:27], v[156:159], v[180:183], v[24:27]
	v_mfma_f32_16x16x32_bf16 v[12:15], v[148:151], v[188:191], v[12:15]
	v_mfma_f32_16x16x32_bf16 v[8:11], v[156:159], v[188:191], v[8:11]
	s_barrier
	s_setprio 0
	s_add_u32 s69, s69, 0x100
	s_addc_u32 s70, s70, 0
	s_add_u32 s44, s44, 0x100
	s_addc_u32 s45, s45, 0
	s_cmp_ge_u32 s71, s67
	s_mov_b32 s46, s71
	s_cbranch_scc0 .LBB0_2020
	v_readlane_b32 s44, v254, 27
	v_readlane_b32 s45, v254, 28
	s_and_b64 vcc, exec, s[44:45]
	s_cbranch_vccz .LBB0_2028
	s_barrier
	s_cmp_lt_i32 s14, 0
	s_mov_b64 s[44:45], -1
	s_cbranch_scc1 .LBB0_2029

.LBB0_2289:
	ds_read_b128 v[148:151], v159
	ds_read_b128 v[164:167], v159 offset:1024
	ds_read_b128 v[168:171], v159 offset:2048
	ds_read_b128 v[172:175], v159 offset:3072
	ds_read_b128 v[176:179], v160
	ds_read_b128 v[180:183], v160 offset:1024
	ds_read_b128 v[184:187], v160 offset:2048
	ds_read_b128 v[188:191], v160 offset:3072
	s_add_i32 s87, s46, 2
	s_add_u32 s47, s44, 0xfff00080
	s_addc_u32 s48, s45, -1
	s_cmp_eq_u32 s43, s46
	s_cselect_b32 s46, s25, s85
	s_cselect_b32 s49, s37, s48
	s_cselect_b32 s48, s36, s47
	s_cselect_b32 s47, s5, s86
	v_lshl_add_u64 v[152:153], s[44:45], 0, v[142:143]
	s_add_i32 m0, s94, 0xc000
	ds_read_b128 v[192:195], v161
	ds_read_b128 v[196:199], v161 offset:1024
	ds_read_b128 v[200:203], v161 offset:2048
	ds_read_b128 v[204:207], v161 offset:3072
	ds_read_b128 v[208:211], v161 offset:4096
	ds_read_b128 v[212:215], v161 offset:5120
	ds_read_b128 v[216:219], v161 offset:6144
	ds_read_b128 v[220:223], v161 offset:7168
	global_load_lds_dwordx4 v[152:153], off
	v_lshl_add_u64 v[152:153], s[44:45], 0, v[144:145]
	s_add_i32 m0, s94, 0xe000
	s_nop 0
	global_load_lds_dwordx4 v[152:153], off
	s_waitcnt vmcnt(8)
	s_waitcnt lgkmcnt(0)
	.p2alignl 3, 3212836864
	s_setprio 1
	s_barrier
	v_mfma_f32_16x16x32_bf16 v[112:115], v[148:151], v[192:195], v[112:115]
	v_mfma_f32_16x16x32_bf16 v[116:119], v[168:171], v[192:195], v[116:119]
	v_mfma_f32_16x16x32_bf16 v[100:103], v[148:151], v[200:203], v[100:103]
	v_mfma_f32_16x16x32_bf16 v[96:99], v[168:171], v[200:203], v[96:99]
	v_mfma_f32_16x16x32_bf16 v[84:87], v[148:151], v[208:211], v[84:87]
	v_mfma_f32_16x16x32_bf16 v[80:83], v[168:171], v[208:211], v[80:83]
	v_mfma_f32_16x16x32_bf16 v[52:55], v[148:151], v[216:219], v[52:55]
	v_mfma_f32_16x16x32_bf16 v[48:51], v[168:171], v[216:219], v[48:51]
	v_mfma_f32_16x16x32_bf16 v[112:115], v[164:167], v[196:199], v[112:115]
	v_mfma_f32_16x16x32_bf16 v[116:119], v[172:175], v[196:199], v[116:119]
	v_mfma_f32_16x16x32_bf16 v[100:103], v[164:167], v[204:207], v[100:103]
	v_mfma_f32_16x16x32_bf16 v[96:99], v[172:175], v[204:207], v[96:99]
	v_mfma_f32_16x16x32_bf16 v[84:87], v[164:167], v[212:215], v[84:87]
	v_mfma_f32_16x16x32_bf16 v[80:83], v[172:175], v[212:215], v[80:83]
	v_mfma_f32_16x16x32_bf16 v[52:55], v[164:167], v[220:223], v[52:55]
	v_mfma_f32_16x16x32_bf16 v[48:51], v[172:175], v[220:223], v[48:51]
	s_setprio 0
	s_setprio 1
	v_mfma_f32_16x16x32_bf16 v[124:127], v[176:179], v[192:195], v[124:127]
	v_mfma_f32_16x16x32_bf16 v[120:123], v[184:187], v[192:195], v[120:123]
	v_mfma_f32_16x16x32_bf16 v[108:111], v[176:179], v[200:203], v[108:111]
	v_mfma_f32_16x16x32_bf16 v[104:107], v[184:187], v[200:203], v[104:107]
	v_mfma_f32_16x16x32_bf16 v[92:95], v[176:179], v[208:211], v[92:95]
	v_mfma_f32_16x16x32_bf16 v[88:91], v[184:187], v[208:211], v[88:91]
	v_mfma_f32_16x16x32_bf16 v[68:71], v[176:179], v[216:219], v[68:71]
	v_mfma_f32_16x16x32_bf16 v[64:67], v[184:187], v[216:219], v[64:67]
	v_mfma_f32_16x16x32_bf16 v[124:127], v[180:183], v[196:199], v[124:127]
	v_mfma_f32_16x16x32_bf16 v[120:123], v[188:191], v[196:199], v[120:123]
	v_mfma_f32_16x16x32_bf16 v[108:111], v[180:183], v[204:207], v[108:111]
	v_mfma_f32_16x16x32_bf16 v[104:107], v[188:191], v[204:207], v[104:107]
	v_mfma_f32_16x16x32_bf16 v[92:95], v[180:183], v[212:215], v[92:95]
	v_mfma_f32_16x16x32_bf16 v[88:91], v[188:191], v[212:215], v[88:91]
	v_mfma_f32_16x16x32_bf16 v[68:71], v[180:183], v[220:223], v[68:71]
	v_mfma_f32_16x16x32_bf16 v[64:67], v[188:191], v[220:223], v[64:67]
	s_barrier
	s_setprio 0
	s_add_i32 s88, s77, s97
	v_lshl_add_u64 v[152:153], s[46:47], 0, v[132:133]
	s_mov_b32 m0, s88
	ds_read_b128 v[192:195], v161 offset:16384
	ds_read_b128 v[196:199], v161 offset:17408
	ds_read_b128 v[200:203], v161 offset:18432
	ds_read_b128 v[204:207], v161 offset:19456
	ds_read_b128 v[208:211], v161 offset:20480
	ds_read_b128 v[212:215], v161 offset:21504
	ds_read_b128 v[216:219], v161 offset:22528
	ds_read_b128 v[220:223], v161 offset:23552
	global_load_lds_dwordx4 v[152:153], off
	s_add_i32 m0, s88, 0x2000
	s_add_u32 s88, s46, 0x100000
	v_lshl_add_u64 v[224:225], s[46:47], 0, v[136:137]
	s_addc_u32 s89, s47, 0
	s_add_i32 s90, s78, s97
	global_load_lds_dwordx4 v[224:225], off
	v_lshl_add_u64 v[226:227], s[88:89], 0, v[132:133]
	s_mov_b32 m0, s90
	v_lshl_add_u64 v[228:229], s[48:49], 0, v[134:135]
	global_load_lds_dwordx4 v[226:227], off
	v_lshl_add_u64 v[226:227], s[88:89], 0, v[136:137]
	s_add_i32 m0, s90, 0x2000
	s_nop 0
	global_load_lds_dwordx4 v[226:227], off
	v_lshl_add_u64 v[226:227], s[48:49], 0, v[130:131]
	s_mov_b32 m0, s94
	s_nop 0
	global_load_lds_dwordx4 v[226:227], off
	s_mov_b32 m0, s52
	s_nop 0
	global_load_lds_dwordx4 v[228:229], off
	s_waitcnt vmcnt(8)
	s_waitcnt lgkmcnt(0)
	.p2alignl 3, 3212836864
	s_setprio 1
	s_barrier
	v_mfma_f32_16x16x32_bf16 v[60:63], v[148:151], v[192:195], v[60:63]
	v_mfma_f32_16x16x32_bf16 v[56:59], v[168:171], v[192:195], v[56:59]
	v_mfma_f32_16x16x32_bf16 v[36:39], v[148:151], v[200:203], v[36:39]
	v_mfma_f32_16x16x32_bf16 v[32:35], v[168:171], v[200:203], v[32:35]
	v_mfma_f32_16x16x32_bf16 v[20:23], v[148:151], v[208:211], v[20:23]
	v_mfma_f32_16x16x32_bf16 v[16:19], v[168:171], v[208:211], v[16:19]
	v_mfma_f32_16x16x32_bf16 v[4:7], v[148:151], v[216:219], v[4:7]
	v_mfma_f32_16x16x32_bf16 v[0:3], v[168:171], v[216:219], v[0:3]
	v_mfma_f32_16x16x32_bf16 v[60:63], v[164:167], v[196:199], v[60:63]
	v_mfma_f32_16x16x32_bf16 v[56:59], v[172:175], v[196:199], v[56:59]
	v_mfma_f32_16x16x32_bf16 v[36:39], v[164:167], v[204:207], v[36:39]
	v_mfma_f32_16x16x32_bf16 v[32:35], v[172:175], v[204:207], v[32:35]
	v_mfma_f32_16x16x32_bf16 v[20:23], v[164:167], v[212:215], v[20:23]
	v_mfma_f32_16x16x32_bf16 v[16:19], v[172:175], v[212:215], v[16:19]
	v_mfma_f32_16x16x32_bf16 v[4:7], v[164:167], v[220:223], v[4:7]
	v_mfma_f32_16x16x32_bf16 v[0:3], v[172:175], v[220:223], v[0:3]
	s_setprio 0
	s_setprio 1
	v_mfma_f32_16x16x32_bf16 v[76:79], v[176:179], v[192:195], v[76:79]
	v_mfma_f32_16x16x32_bf16 v[72:75], v[184:187], v[192:195], v[72:75]
	v_mfma_f32_16x16x32_bf16 v[44:47], v[176:179], v[200:203], v[44:47]
	v_mfma_f32_16x16x32_bf16 v[40:43], v[184:187], v[200:203], v[40:43]
	v_mfma_f32_16x16x32_bf16 v[28:31], v[176:179], v[208:211], v[28:31]
	v_mfma_f32_16x16x32_bf16 v[24:27], v[184:187], v[208:211], v[24:27]
	v_mfma_f32_16x16x32_bf16 v[12:15], v[176:179], v[216:219], v[12:15]
	v_mfma_f32_16x16x32_bf16 v[8:11], v[184:187], v[216:219], v[8:11]
	v_mfma_f32_16x16x32_bf16 v[76:79], v[180:183], v[196:199], v[76:79]
	v_mfma_f32_16x16x32_bf16 v[72:75], v[188:191], v[196:199], v[72:75]
	v_mfma_f32_16x16x32_bf16 v[44:47], v[180:183], v[204:207], v[44:47]
	v_mfma_f32_16x16x32_bf16 v[40:43], v[188:191], v[204:207], v[40:43]
	v_mfma_f32_16x16x32_bf16 v[28:31], v[180:183], v[212:215], v[28:31]
	v_mfma_f32_16x16x32_bf16 v[24:27], v[188:191], v[212:215], v[24:27]
	v_mfma_f32_16x16x32_bf16 v[12:15], v[180:183], v[220:223], v[12:15]
	v_mfma_f32_16x16x32_bf16 v[8:11], v[188:191], v[220:223], v[8:11]
	s_barrier
	s_setprio 0
	s_add_i32 s88, 0, 0x18000
	v_add_u32_e32 v163, s88, v157
	s_add_i32 s89, 0, 0x1c000
	ds_read_b128 v[148:151], v163
	ds_read_b128 v[164:167], v163 offset:1024
	ds_read_b128 v[168:171], v163 offset:2048
	ds_read_b128 v[172:175], v163 offset:3072
	v_add_u32_e32 v163, s89, v157
	ds_read_b128 v[176:179], v163
	ds_read_b128 v[180:183], v163 offset:1024
	ds_read_b128 v[184:187], v163 offset:2048
	ds_read_b128 v[188:191], v163 offset:3072
	s_add_u32 s48, s48, 0x100000
	s_addc_u32 s49, s49, 0
	s_mov_b32 m0, s53
	v_lshl_add_u64 v[230:231], s[48:49], 0, v[130:131]
	ds_read_b128 v[192:195], v161 offset:32768
	ds_read_b128 v[196:199], v161 offset:33792
	ds_read_b128 v[200:203], v161 offset:34816
	ds_read_b128 v[204:207], v161 offset:35840
	ds_read_b128 v[208:211], v161 offset:36864
	ds_read_b128 v[212:215], v161 offset:37888
	ds_read_b128 v[216:219], v161 offset:38912
	ds_read_b128 v[220:223], v161 offset:39936
	global_load_lds_dwordx4 v[230:231], off
	v_lshl_add_u64 v[230:231], s[48:49], 0, v[134:135]
	s_mov_b32 m0, s54
	s_nop 0
	global_load_lds_dwordx4 v[230:231], off
	s_waitcnt vmcnt(8)
	s_waitcnt lgkmcnt(0)
	.p2alignl 3, 3212836864
	s_setprio 1
	s_barrier
	v_mfma_f32_16x16x32_bf16 v[112:115], v[148:151], v[192:195], v[112:115]
	v_mfma_f32_16x16x32_bf16 v[116:119], v[168:171], v[192:195], v[116:119]
	v_mfma_f32_16x16x32_bf16 v[100:103], v[148:151], v[200:203], v[100:103]
	v_mfma_f32_16x16x32_bf16 v[96:99], v[168:171], v[200:203], v[96:99]
	v_mfma_f32_16x16x32_bf16 v[84:87], v[148:151], v[208:211], v[84:87]
	v_mfma_f32_16x16x32_bf16 v[80:83], v[168:171], v[208:211], v[80:83]
	v_mfma_f32_16x16x32_bf16 v[52:55], v[148:151], v[216:219], v[52:55]
	v_mfma_f32_16x16x32_bf16 v[48:51], v[168:171], v[216:219], v[48:51]
	v_mfma_f32_16x16x32_bf16 v[112:115], v[164:167], v[196:199], v[112:115]
	v_mfma_f32_16x16x32_bf16 v[116:119], v[172:175], v[196:199], v[116:119]
	v_mfma_f32_16x16x32_bf16 v[100:103], v[164:167], v[204:207], v[100:103]
	v_mfma_f32_16x16x32_bf16 v[96:99], v[172:175], v[204:207], v[96:99]
	v_mfma_f32_16x16x32_bf16 v[84:87], v[164:167], v[212:215], v[84:87]
	v_mfma_f32_16x16x32_bf16 v[80:83], v[172:175], v[212:215], v[80:83]
	v_mfma_f32_16x16x32_bf16 v[52:55], v[164:167], v[220:223], v[52:55]
	v_mfma_f32_16x16x32_bf16 v[48:51], v[172:175], v[220:223], v[48:51]
	s_setprio 0
	s_setprio 1
	v_mfma_f32_16x16x32_bf16 v[124:127], v[176:179], v[192:195], v[124:127]
	v_mfma_f32_16x16x32_bf16 v[120:123], v[184:187], v[192:195], v[120:123]
	v_mfma_f32_16x16x32_bf16 v[108:111], v[176:179], v[200:203], v[108:111]
	v_mfma_f32_16x16x32_bf16 v[104:107], v[184:187], v[200:203], v[104:107]
	v_mfma_f32_16x16x32_bf16 v[92:95], v[176:179], v[208:211], v[92:95]
	v_mfma_f32_16x16x32_bf16 v[88:91], v[184:187], v[208:211], v[88:91]
	v_mfma_f32_16x16x32_bf16 v[68:71], v[176:179], v[216:219], v[68:71]
	v_mfma_f32_16x16x32_bf16 v[64:67], v[184:187], v[216:219], v[64:67]
	v_mfma_f32_16x16x32_bf16 v[124:127], v[180:183], v[196:199], v[124:127]
	v_mfma_f32_16x16x32_bf16 v[120:123], v[188:191], v[196:199], v[120:123]
	v_mfma_f32_16x16x32_bf16 v[108:111], v[180:183], v[204:207], v[108:111]
	v_mfma_f32_16x16x32_bf16 v[104:107], v[188:191], v[204:207], v[104:107]
	v_mfma_f32_16x16x32_bf16 v[92:95], v[180:183], v[212:215], v[92:95]
	v_mfma_f32_16x16x32_bf16 v[88:91], v[188:191], v[212:215], v[88:91]
	v_mfma_f32_16x16x32_bf16 v[68:71], v[180:183], v[220:223], v[68:71]
	v_mfma_f32_16x16x32_bf16 v[64:67], v[188:191], v[220:223], v[64:67]
	s_barrier
	s_setprio 0
	s_add_i32 s48, s88, s97
	v_lshl_add_u64 v[152:153], v[152:153], 0, s[18:19]
	s_mov_b32 m0, s48
	ds_read_b128 v[192:195], v161 offset:49152
	ds_read_b128 v[196:199], v161 offset:50176
	ds_read_b128 v[200:203], v161 offset:51200
	ds_read_b128 v[204:207], v161 offset:52224
	ds_read_b128 v[208:211], v161 offset:53248
	ds_read_b128 v[212:215], v161 offset:54272
	ds_read_b128 v[216:219], v161 offset:55296
	ds_read_b128 v[220:223], v161 offset:56320
	global_load_lds_dwordx4 v[152:153], off
	s_add_i32 m0, s48, 0x2000
	s_add_u32 s46, s46, 0x100080
	v_lshl_add_u64 v[152:153], v[224:225], 0, s[18:19]
	s_addc_u32 s47, s47, 0
	s_add_i32 s48, s89, s97
	global_load_lds_dwordx4 v[152:153], off
	v_lshl_add_u64 v[152:153], s[46:47], 0, v[132:133]
	s_mov_b32 m0, s48
	s_nop 0
	global_load_lds_dwordx4 v[152:153], off
	v_lshl_add_u64 v[152:153], s[46:47], 0, v[136:137]
	s_add_i32 m0, s48, 0x2000
	s_nop 0
	global_load_lds_dwordx4 v[152:153], off
	v_lshl_add_u64 v[152:153], v[226:227], 0, s[18:19]
	s_mov_b32 m0, s68
	s_nop 0
	global_load_lds_dwordx4 v[152:153], off
	v_lshl_add_u64 v[152:153], v[228:229], 0, s[18:19]
	s_mov_b32 m0, s69
	s_nop 0
	global_load_lds_dwordx4 v[152:153], off
	s_waitcnt vmcnt(8)
	s_waitcnt lgkmcnt(0)
	.p2alignl 3, 3212836864
	s_setprio 1
	s_barrier
	v_mfma_f32_16x16x32_bf16 v[60:63], v[148:151], v[192:195], v[60:63]
	v_mfma_f32_16x16x32_bf16 v[56:59], v[168:171], v[192:195], v[56:59]
	v_mfma_f32_16x16x32_bf16 v[36:39], v[148:151], v[200:203], v[36:39]
	v_mfma_f32_16x16x32_bf16 v[32:35], v[168:171], v[200:203], v[32:35]
	v_mfma_f32_16x16x32_bf16 v[20:23], v[148:151], v[208:211], v[20:23]
	v_mfma_f32_16x16x32_bf16 v[16:19], v[168:171], v[208:211], v[16:19]
	v_mfma_f32_16x16x32_bf16 v[4:7], v[148:151], v[216:219], v[4:7]
	v_mfma_f32_16x16x32_bf16 v[0:3], v[168:171], v[216:219], v[0:3]
	v_mfma_f32_16x16x32_bf16 v[60:63], v[164:167], v[196:199], v[60:63]
	v_mfma_f32_16x16x32_bf16 v[56:59], v[172:175], v[196:199], v[56:59]
	v_mfma_f32_16x16x32_bf16 v[36:39], v[164:167], v[204:207], v[36:39]
	v_mfma_f32_16x16x32_bf16 v[32:35], v[172:175], v[204:207], v[32:35]
	v_mfma_f32_16x16x32_bf16 v[20:23], v[164:167], v[212:215], v[20:23]
	v_mfma_f32_16x16x32_bf16 v[16:19], v[172:175], v[212:215], v[16:19]
	v_mfma_f32_16x16x32_bf16 v[4:7], v[164:167], v[220:223], v[4:7]
	v_mfma_f32_16x16x32_bf16 v[0:3], v[172:175], v[220:223], v[0:3]
	s_setprio 0
	s_setprio 1
	v_mfma_f32_16x16x32_bf16 v[76:79], v[176:179], v[192:195], v[76:79]
	v_mfma_f32_16x16x32_bf16 v[72:75], v[184:187], v[192:195], v[72:75]
	v_mfma_f32_16x16x32_bf16 v[44:47], v[176:179], v[200:203], v[44:47]
	v_mfma_f32_16x16x32_bf16 v[40:43], v[184:187], v[200:203], v[40:43]
	v_mfma_f32_16x16x32_bf16 v[28:31], v[176:179], v[208:211], v[28:31]
	v_mfma_f32_16x16x32_bf16 v[24:27], v[184:187], v[208:211], v[24:27]
	v_mfma_f32_16x16x32_bf16 v[12:15], v[176:179], v[216:219], v[12:15]
	v_mfma_f32_16x16x32_bf16 v[8:11], v[184:187], v[216:219], v[8:11]
	v_mfma_f32_16x16x32_bf16 v[76:79], v[180:183], v[196:199], v[76:79]
	v_mfma_f32_16x16x32_bf16 v[72:75], v[188:191], v[196:199], v[72:75]
	v_mfma_f32_16x16x32_bf16 v[44:47], v[180:183], v[204:207], v[44:47]
	v_mfma_f32_16x16x32_bf16 v[40:43], v[188:191], v[204:207], v[40:43]
	v_mfma_f32_16x16x32_bf16 v[28:31], v[180:183], v[212:215], v[28:31]
	v_mfma_f32_16x16x32_bf16 v[24:27], v[188:191], v[212:215], v[24:27]
	v_mfma_f32_16x16x32_bf16 v[12:15], v[180:183], v[220:223], v[12:15]
	v_mfma_f32_16x16x32_bf16 v[8:11], v[188:191], v[220:223], v[8:11]
	s_barrier
	s_setprio 0
	s_add_u32 s85, s85, 0x100
	s_addc_u32 s86, s86, 0
	s_add_u32 s44, s44, 0x100
	s_addc_u32 s45, s45, 0
	s_cmp_ge_u32 s87, s84
	s_mov_b32 s46, s87
	s_cbranch_scc0 .LBB0_2289
	v_readlane_b32 s44, v254, 27
	v_readlane_b32 s45, v254, 28
	s_and_b64 vcc, exec, s[44:45]
	s_cbranch_vccz .LBB0_2297
	s_barrier
	s_cmp_lt_i32 s16, 0
	s_mov_b64 s[44:45], -1
	s_cbranch_scc1 .LBB0_2298

.LBB0_2453:
	ds_read_b128 v[128:131], v228
	ds_read_b128 v[132:135], v228 offset:1024
	ds_read_b128 v[136:139], v228 offset:2048
	ds_read_b128 v[140:143], v228 offset:3072
	ds_read_b128 v[144:147], v229
	ds_read_b128 v[148:151], v229 offset:1024
	ds_read_b128 v[152:155], v229 offset:2048
	ds_read_b128 v[156:159], v229 offset:3072
	s_add_i32 s79, s46, 2
	s_add_u32 s47, s44, 0xffc00080
	s_addc_u32 s48, s45, -1
	s_cmp_eq_u32 s75, s46
	s_cselect_b32 s46, s43, s77
	s_cselect_b32 s49, s35, s48
	s_cselect_b32 s48, s41, s47
	s_cselect_b32 s47, s31, s78
	v_lshl_add_u64 v[208:209], s[44:45], 0, v[202:203]
	s_add_i32 m0, s94, 0xc000
	ds_read_b128 v[160:163], v230
	ds_read_b128 v[164:167], v230 offset:1024
	ds_read_b128 v[168:171], v230 offset:2048
	ds_read_b128 v[172:175], v230 offset:3072
	ds_read_b128 v[176:179], v230 offset:4096
	ds_read_b128 v[180:183], v230 offset:5120
	ds_read_b128 v[184:187], v230 offset:6144
	ds_read_b128 v[188:191], v230 offset:7168
	global_load_lds_dwordx4 v[208:209], off
	v_lshl_add_u64 v[208:209], s[44:45], 0, v[204:205]
	s_add_i32 m0, s94, 0xe000
	s_nop 0
	global_load_lds_dwordx4 v[208:209], off
	s_waitcnt vmcnt(8)
	s_waitcnt lgkmcnt(0)
	.p2alignl 3, 3212836864
	s_setprio 1
	s_barrier
	v_mfma_f32_16x16x32_bf16 v[112:115], v[128:131], v[160:163], v[112:115]
	v_mfma_f32_16x16x32_bf16 v[116:119], v[136:139], v[160:163], v[116:119]
	v_mfma_f32_16x16x32_bf16 v[100:103], v[128:131], v[168:171], v[100:103]
	v_mfma_f32_16x16x32_bf16 v[96:99], v[136:139], v[168:171], v[96:99]
	v_mfma_f32_16x16x32_bf16 v[84:87], v[128:131], v[176:179], v[84:87]
	v_mfma_f32_16x16x32_bf16 v[80:83], v[136:139], v[176:179], v[80:83]
	v_mfma_f32_16x16x32_bf16 v[52:55], v[128:131], v[184:187], v[52:55]
	v_mfma_f32_16x16x32_bf16 v[48:51], v[136:139], v[184:187], v[48:51]
	v_mfma_f32_16x16x32_bf16 v[112:115], v[132:135], v[164:167], v[112:115]
	v_mfma_f32_16x16x32_bf16 v[116:119], v[140:143], v[164:167], v[116:119]
	v_mfma_f32_16x16x32_bf16 v[100:103], v[132:135], v[172:175], v[100:103]
	v_mfma_f32_16x16x32_bf16 v[96:99], v[140:143], v[172:175], v[96:99]
	v_mfma_f32_16x16x32_bf16 v[84:87], v[132:135], v[180:183], v[84:87]
	v_mfma_f32_16x16x32_bf16 v[80:83], v[140:143], v[180:183], v[80:83]
	v_mfma_f32_16x16x32_bf16 v[52:55], v[132:135], v[188:191], v[52:55]
	v_mfma_f32_16x16x32_bf16 v[48:51], v[140:143], v[188:191], v[48:51]
	s_setprio 0
	s_setprio 1
	v_mfma_f32_16x16x32_bf16 v[124:127], v[144:147], v[160:163], v[124:127]
	v_mfma_f32_16x16x32_bf16 v[120:123], v[152:155], v[160:163], v[120:123]
	v_mfma_f32_16x16x32_bf16 v[108:111], v[144:147], v[168:171], v[108:111]
	v_mfma_f32_16x16x32_bf16 v[104:107], v[152:155], v[168:171], v[104:107]
	v_mfma_f32_16x16x32_bf16 v[92:95], v[144:147], v[176:179], v[92:95]
	v_mfma_f32_16x16x32_bf16 v[88:91], v[152:155], v[176:179], v[88:91]
	v_mfma_f32_16x16x32_bf16 v[68:71], v[144:147], v[184:187], v[68:71]
	v_mfma_f32_16x16x32_bf16 v[64:67], v[152:155], v[184:187], v[64:67]
	v_mfma_f32_16x16x32_bf16 v[124:127], v[148:151], v[164:167], v[124:127]
	v_mfma_f32_16x16x32_bf16 v[120:123], v[156:159], v[164:167], v[120:123]
	v_mfma_f32_16x16x32_bf16 v[108:111], v[148:151], v[172:175], v[108:111]
	v_mfma_f32_16x16x32_bf16 v[104:107], v[156:159], v[172:175], v[104:107]
	v_mfma_f32_16x16x32_bf16 v[92:95], v[148:151], v[180:183], v[92:95]
	v_mfma_f32_16x16x32_bf16 v[88:91], v[156:159], v[180:183], v[88:91]
	v_mfma_f32_16x16x32_bf16 v[68:71], v[148:151], v[188:191], v[68:71]
	v_mfma_f32_16x16x32_bf16 v[64:67], v[156:159], v[188:191], v[64:67]
	s_barrier
	s_setprio 0
	s_add_i32 s80, s68, s97
	v_lshl_add_u64 v[208:209], s[46:47], 0, v[194:195]
	s_mov_b32 m0, s80
	ds_read_b128 v[160:163], v230 offset:16384
	ds_read_b128 v[164:167], v230 offset:17408
	ds_read_b128 v[168:171], v230 offset:18432
	ds_read_b128 v[172:175], v230 offset:19456
	ds_read_b128 v[176:179], v230 offset:20480
	ds_read_b128 v[180:183], v230 offset:21504
	ds_read_b128 v[184:187], v230 offset:22528
	ds_read_b128 v[188:191], v230 offset:23552
	global_load_lds_dwordx4 v[208:209], off
	s_add_i32 m0, s80, 0x2000
	s_add_u32 s80, s46, 0x400000
	v_lshl_add_u64 v[210:211], s[46:47], 0, v[198:199]
	s_addc_u32 s81, s47, 0
	s_add_i32 s84, s69, s97
	global_load_lds_dwordx4 v[210:211], off
	v_lshl_add_u64 v[212:213], s[80:81], 0, v[194:195]
	s_mov_b32 m0, s84
	v_lshl_add_u64 v[214:215], s[48:49], 0, v[196:197]
	global_load_lds_dwordx4 v[212:213], off
	v_lshl_add_u64 v[212:213], s[80:81], 0, v[198:199]
	s_add_i32 m0, s84, 0x2000
	s_nop 0
	global_load_lds_dwordx4 v[212:213], off
	v_lshl_add_u64 v[212:213], s[48:49], 0, v[192:193]
	s_mov_b32 m0, s94
	s_nop 0
	global_load_lds_dwordx4 v[212:213], off
	s_mov_b32 m0, s51
	s_nop 0
	global_load_lds_dwordx4 v[214:215], off
	s_waitcnt vmcnt(8)
	s_waitcnt lgkmcnt(0)
	.p2alignl 3, 3212836864
	s_setprio 1
	s_barrier
	v_mfma_f32_16x16x32_bf16 v[60:63], v[128:131], v[160:163], v[60:63]
	v_mfma_f32_16x16x32_bf16 v[56:59], v[136:139], v[160:163], v[56:59]
	v_mfma_f32_16x16x32_bf16 v[36:39], v[128:131], v[168:171], v[36:39]
	v_mfma_f32_16x16x32_bf16 v[32:35], v[136:139], v[168:171], v[32:35]
	v_mfma_f32_16x16x32_bf16 v[20:23], v[128:131], v[176:179], v[20:23]
	v_mfma_f32_16x16x32_bf16 v[16:19], v[136:139], v[176:179], v[16:19]
	v_mfma_f32_16x16x32_bf16 v[4:7], v[128:131], v[184:187], v[4:7]
	v_mfma_f32_16x16x32_bf16 v[0:3], v[136:139], v[184:187], v[0:3]
	v_mfma_f32_16x16x32_bf16 v[60:63], v[132:135], v[164:167], v[60:63]
	v_mfma_f32_16x16x32_bf16 v[56:59], v[140:143], v[164:167], v[56:59]
	v_mfma_f32_16x16x32_bf16 v[36:39], v[132:135], v[172:175], v[36:39]
	v_mfma_f32_16x16x32_bf16 v[32:35], v[140:143], v[172:175], v[32:35]
	v_mfma_f32_16x16x32_bf16 v[20:23], v[132:135], v[180:183], v[20:23]
	v_mfma_f32_16x16x32_bf16 v[16:19], v[140:143], v[180:183], v[16:19]
	v_mfma_f32_16x16x32_bf16 v[4:7], v[132:135], v[188:191], v[4:7]
	v_mfma_f32_16x16x32_bf16 v[0:3], v[140:143], v[188:191], v[0:3]
	s_setprio 0
	s_setprio 1
	v_mfma_f32_16x16x32_bf16 v[76:79], v[144:147], v[160:163], v[76:79]
	v_mfma_f32_16x16x32_bf16 v[72:75], v[152:155], v[160:163], v[72:75]
	v_mfma_f32_16x16x32_bf16 v[44:47], v[144:147], v[168:171], v[44:47]
	v_mfma_f32_16x16x32_bf16 v[40:43], v[152:155], v[168:171], v[40:43]
	v_mfma_f32_16x16x32_bf16 v[28:31], v[144:147], v[176:179], v[28:31]
	v_mfma_f32_16x16x32_bf16 v[24:27], v[152:155], v[176:179], v[24:27]
	v_mfma_f32_16x16x32_bf16 v[12:15], v[144:147], v[184:187], v[12:15]
	v_mfma_f32_16x16x32_bf16 v[8:11], v[152:155], v[184:187], v[8:11]
	v_mfma_f32_16x16x32_bf16 v[76:79], v[148:151], v[164:167], v[76:79]
	v_mfma_f32_16x16x32_bf16 v[72:75], v[156:159], v[164:167], v[72:75]
	v_mfma_f32_16x16x32_bf16 v[44:47], v[148:151], v[172:175], v[44:47]
	v_mfma_f32_16x16x32_bf16 v[40:43], v[156:159], v[172:175], v[40:43]
	v_mfma_f32_16x16x32_bf16 v[28:31], v[148:151], v[180:183], v[28:31]
	v_mfma_f32_16x16x32_bf16 v[24:27], v[156:159], v[180:183], v[24:27]
	v_mfma_f32_16x16x32_bf16 v[12:15], v[148:151], v[188:191], v[12:15]
	v_mfma_f32_16x16x32_bf16 v[8:11], v[156:159], v[188:191], v[8:11]
	s_barrier
	s_setprio 0
	s_add_i32 s80, 0, 0x18000
	s_add_i32 s81, 0, 0x1c000
	v_add_u32_e32 v140, s80, v226
	v_add_u32_e32 v156, s81, v226
	ds_read_b128 v[128:131], v140
	ds_read_b128 v[132:135], v140 offset:1024
	ds_read_b128 v[136:139], v140 offset:2048
	ds_read_b128 v[140:143], v140 offset:3072
	ds_read_b128 v[144:147], v156
	ds_read_b128 v[148:151], v156 offset:1024
	ds_read_b128 v[152:155], v156 offset:2048
	ds_read_b128 v[156:159], v156 offset:3072
	s_add_u32 s48, s48, 0x400000
	s_addc_u32 s49, s49, 0
	s_mov_b32 m0, s52
	v_lshl_add_u64 v[216:217], s[48:49], 0, v[192:193]
	ds_read_b128 v[160:163], v230 offset:32768
	ds_read_b128 v[164:167], v230 offset:33792
	ds_read_b128 v[168:171], v230 offset:34816
	ds_read_b128 v[172:175], v230 offset:35840
	ds_read_b128 v[176:179], v230 offset:36864
	ds_read_b128 v[180:183], v230 offset:37888
	ds_read_b128 v[184:187], v230 offset:38912
	ds_read_b128 v[188:191], v230 offset:39936
	global_load_lds_dwordx4 v[216:217], off
	v_lshl_add_u64 v[216:217], s[48:49], 0, v[196:197]
	s_mov_b32 m0, s53
	s_nop 0
	global_load_lds_dwordx4 v[216:217], off
	s_waitcnt vmcnt(8)
	s_waitcnt lgkmcnt(0)
	.p2alignl 3, 3212836864
	s_setprio 1
	s_barrier
	v_mfma_f32_16x16x32_bf16 v[112:115], v[128:131], v[160:163], v[112:115]
	v_mfma_f32_16x16x32_bf16 v[116:119], v[136:139], v[160:163], v[116:119]
	v_mfma_f32_16x16x32_bf16 v[100:103], v[128:131], v[168:171], v[100:103]
	v_mfma_f32_16x16x32_bf16 v[96:99], v[136:139], v[168:171], v[96:99]
	v_mfma_f32_16x16x32_bf16 v[84:87], v[128:131], v[176:179], v[84:87]
	v_mfma_f32_16x16x32_bf16 v[80:83], v[136:139], v[176:179], v[80:83]
	v_mfma_f32_16x16x32_bf16 v[52:55], v[128:131], v[184:187], v[52:55]
	v_mfma_f32_16x16x32_bf16 v[48:51], v[136:139], v[184:187], v[48:51]
	v_mfma_f32_16x16x32_bf16 v[112:115], v[132:135], v[164:167], v[112:115]
	v_mfma_f32_16x16x32_bf16 v[116:119], v[140:143], v[164:167], v[116:119]
	v_mfma_f32_16x16x32_bf16 v[100:103], v[132:135], v[172:175], v[100:103]
	v_mfma_f32_16x16x32_bf16 v[96:99], v[140:143], v[172:175], v[96:99]
	v_mfma_f32_16x16x32_bf16 v[84:87], v[132:135], v[180:183], v[84:87]
	v_mfma_f32_16x16x32_bf16 v[80:83], v[140:143], v[180:183], v[80:83]
	v_mfma_f32_16x16x32_bf16 v[52:55], v[132:135], v[188:191], v[52:55]
	v_mfma_f32_16x16x32_bf16 v[48:51], v[140:143], v[188:191], v[48:51]
	s_setprio 0
	s_setprio 1
	v_mfma_f32_16x16x32_bf16 v[124:127], v[144:147], v[160:163], v[124:127]
	v_mfma_f32_16x16x32_bf16 v[120:123], v[152:155], v[160:163], v[120:123]
	v_mfma_f32_16x16x32_bf16 v[108:111], v[144:147], v[168:171], v[108:111]
	v_mfma_f32_16x16x32_bf16 v[104:107], v[152:155], v[168:171], v[104:107]
	v_mfma_f32_16x16x32_bf16 v[92:95], v[144:147], v[176:179], v[92:95]
	v_mfma_f32_16x16x32_bf16 v[88:91], v[152:155], v[176:179], v[88:91]
	v_mfma_f32_16x16x32_bf16 v[68:71], v[144:147], v[184:187], v[68:71]
	v_mfma_f32_16x16x32_bf16 v[64:67], v[152:155], v[184:187], v[64:67]
	v_mfma_f32_16x16x32_bf16 v[124:127], v[148:151], v[164:167], v[124:127]
	v_mfma_f32_16x16x32_bf16 v[120:123], v[156:159], v[164:167], v[120:123]
	v_mfma_f32_16x16x32_bf16 v[108:111], v[148:151], v[172:175], v[108:111]
	v_mfma_f32_16x16x32_bf16 v[104:107], v[156:159], v[172:175], v[104:107]
	v_mfma_f32_16x16x32_bf16 v[92:95], v[148:151], v[180:183], v[92:95]
	v_mfma_f32_16x16x32_bf16 v[88:91], v[156:159], v[180:183], v[88:91]
	v_mfma_f32_16x16x32_bf16 v[68:71], v[148:151], v[188:191], v[68:71]
	v_mfma_f32_16x16x32_bf16 v[64:67], v[156:159], v[188:191], v[64:67]
	s_barrier
	s_setprio 0
	s_add_i32 s48, s80, s97
	v_lshl_add_u64 v[208:209], v[208:209], 0, s[12:13]
	s_mov_b32 m0, s48
	ds_read_b128 v[160:163], v230 offset:49152
	ds_read_b128 v[164:167], v230 offset:50176
	ds_read_b128 v[168:171], v230 offset:51200
	ds_read_b128 v[172:175], v230 offset:52224
	ds_read_b128 v[176:179], v230 offset:53248
	ds_read_b128 v[180:183], v230 offset:54272
	ds_read_b128 v[184:187], v230 offset:55296
	ds_read_b128 v[188:191], v230 offset:56320
	global_load_lds_dwordx4 v[208:209], off
	s_add_i32 m0, s48, 0x2000
	s_add_u32 s46, s46, 0x400080
	v_lshl_add_u64 v[208:209], v[210:211], 0, s[12:13]
	s_addc_u32 s47, s47, 0
	s_add_i32 s48, s81, s97
	global_load_lds_dwordx4 v[208:209], off
	v_lshl_add_u64 v[208:209], s[46:47], 0, v[194:195]
	s_mov_b32 m0, s48
	s_nop 0
	global_load_lds_dwordx4 v[208:209], off
	v_lshl_add_u64 v[208:209], s[46:47], 0, v[198:199]
	s_add_i32 m0, s48, 0x2000
	s_nop 0
	global_load_lds_dwordx4 v[208:209], off
	v_lshl_add_u64 v[208:209], v[212:213], 0, s[12:13]
	s_mov_b32 m0, s54
	s_nop 0
	global_load_lds_dwordx4 v[208:209], off
	v_lshl_add_u64 v[208:209], v[214:215], 0, s[12:13]
	s_mov_b32 m0, s55
	s_nop 0
	global_load_lds_dwordx4 v[208:209], off
	s_waitcnt vmcnt(8)
	s_waitcnt lgkmcnt(0)
	.p2alignl 3, 3212836864
	s_setprio 1
	s_barrier
	v_mfma_f32_16x16x32_bf16 v[60:63], v[128:131], v[160:163], v[60:63]
	v_mfma_f32_16x16x32_bf16 v[56:59], v[136:139], v[160:163], v[56:59]
	v_mfma_f32_16x16x32_bf16 v[36:39], v[128:131], v[168:171], v[36:39]
	v_mfma_f32_16x16x32_bf16 v[32:35], v[136:139], v[168:171], v[32:35]
	v_mfma_f32_16x16x32_bf16 v[20:23], v[128:131], v[176:179], v[20:23]
	v_mfma_f32_16x16x32_bf16 v[16:19], v[136:139], v[176:179], v[16:19]
	v_mfma_f32_16x16x32_bf16 v[4:7], v[128:131], v[184:187], v[4:7]
	v_mfma_f32_16x16x32_bf16 v[0:3], v[136:139], v[184:187], v[0:3]
	v_mfma_f32_16x16x32_bf16 v[60:63], v[132:135], v[164:167], v[60:63]
	v_mfma_f32_16x16x32_bf16 v[56:59], v[140:143], v[164:167], v[56:59]
	v_mfma_f32_16x16x32_bf16 v[36:39], v[132:135], v[172:175], v[36:39]
	v_mfma_f32_16x16x32_bf16 v[32:35], v[140:143], v[172:175], v[32:35]
	v_mfma_f32_16x16x32_bf16 v[20:23], v[132:135], v[180:183], v[20:23]
	v_mfma_f32_16x16x32_bf16 v[16:19], v[140:143], v[180:183], v[16:19]
	v_mfma_f32_16x16x32_bf16 v[4:7], v[132:135], v[188:191], v[4:7]
	v_mfma_f32_16x16x32_bf16 v[0:3], v[140:143], v[188:191], v[0:3]
	s_setprio 0
	s_setprio 1
	v_mfma_f32_16x16x32_bf16 v[76:79], v[144:147], v[160:163], v[76:79]
	v_mfma_f32_16x16x32_bf16 v[72:75], v[152:155], v[160:163], v[72:75]
	v_mfma_f32_16x16x32_bf16 v[44:47], v[144:147], v[168:171], v[44:47]
	v_mfma_f32_16x16x32_bf16 v[40:43], v[152:155], v[168:171], v[40:43]
	v_mfma_f32_16x16x32_bf16 v[28:31], v[144:147], v[176:179], v[28:31]
	v_mfma_f32_16x16x32_bf16 v[24:27], v[152:155], v[176:179], v[24:27]
	v_mfma_f32_16x16x32_bf16 v[12:15], v[144:147], v[184:187], v[12:15]
	v_mfma_f32_16x16x32_bf16 v[8:11], v[152:155], v[184:187], v[8:11]
	v_mfma_f32_16x16x32_bf16 v[76:79], v[148:151], v[164:167], v[76:79]
	v_mfma_f32_16x16x32_bf16 v[72:75], v[156:159], v[164:167], v[72:75]
	v_mfma_f32_16x16x32_bf16 v[44:47], v[148:151], v[172:175], v[44:47]
	v_mfma_f32_16x16x32_bf16 v[40:43], v[156:159], v[172:175], v[40:43]
	v_mfma_f32_16x16x32_bf16 v[28:31], v[148:151], v[180:183], v[28:31]
	v_mfma_f32_16x16x32_bf16 v[24:27], v[156:159], v[180:183], v[24:27]
	v_mfma_f32_16x16x32_bf16 v[12:15], v[148:151], v[188:191], v[12:15]
	v_mfma_f32_16x16x32_bf16 v[8:11], v[156:159], v[188:191], v[8:11]
	s_barrier
	s_setprio 0
	s_add_u32 s77, s77, 0x100
	s_addc_u32 s78, s78, 0
	s_add_u32 s44, s44, 0x100
	s_addc_u32 s45, s45, 0
	s_cmp_ge_u32 s79, s76
	s_mov_b32 s46, s79
	s_cbranch_scc0 .LBB0_2453
	v_readlane_b32 s44, v254, 27
	v_readlane_b32 s45, v254, 28
	s_and_b64 vcc, exec, s[44:45]
	s_cbranch_vccz .LBB0_2461
	s_barrier
	s_cmp_lt_i32 s10, 0
	s_mov_b64 s[44:45], -1
	s_cbranch_scc1 .LBB0_2462
